# FFN-up epilogues read the RMS partials from a 16 KB LDS copy brought in by LDS-DMA during the unit's first K-loop iteration (no vmcnt(0) drain at epilogue start); static LDS 16 KB
# speedup vs baseline: 1.0074x; 1.0016x over previous
; #define PG8_STAGE(bufoff, gbase, soff, voff) do { _Pragma("unroll") for (int _i = 0; _i < 2; ++_i) \
;         __builtin_amdgcn_global_load_lds((const unsigned*)(((gbase) + (size_t)(unsigned)(soff)) + (voff)[_i]), (LAS unsigned*)(lds + (bufoff) + ldsw + _i * 8192), 16, 0, 0); } while (0)
; #define PG8_LDA(dst, b, h) do { _Pragma("unroll") for (int m = 0; m < 4; ++m) _Pragma("unroll") for (int k = 0; k < 2; ++k) dst[m][k] = *(const LAS bf16x8*)(lds + PG8_SA(b, h) + aoff + m * 2048 + k * 1024); } while (0)
; #define PG8_LDB(dst, b, h) do { _Pragma("unroll") for (int n = 0; n < 2; ++n) _Pragma("unroll") for (int k = 0; k < 2; ++k) dst[n][k] = *(const LAS bf16x8*)(lds + PG8_SB(b, h) + boff + n * 2048 + k * 1024); } while (0)
; #define PG8_MMA(ai, bj, At, Bt) do { __builtin_amdgcn_s_setprio(1); _Pragma("unroll") for (int m = 0; m < 4; ++m) _Pragma("unroll") for (int n = 0; n < 2; ++n) _Pragma("unroll") for (int k = 0; k < 2; ++k) \
;         acc[ai][bj][m][n] = __builtin_amdgcn_mfma_f32_16x16x32_bf16(Bt[n][k], At[m][k], acc[ai][bj][m][n], 0, 0, 0); __builtin_amdgcn_s_setprio(0); } while (0)
; #define PG8_WAIT_V(n) asm volatile("s_waitcnt vmcnt(" #n ")" ::: "memory")
; #define PG8_WAIT_L(n) asm volatile("s_waitcnt lgkmcnt(" #n ")" ::: "memory")
; #define PG8_BAR __builtin_amdgcn_s_barrier()
; #define PG8_SCHED __builtin_amdgcn_sched_barrier(0)
; template <class Epi>
; __device__ __forceinline__ void gemm_phase(LAS unsigned char* lds, const Gemm g, const StaticOrder& S, const Epi& E, const int tid) {
;     ...
;             PG8_LDB(B0, 0, 0); PG8_SCHED; PG8_LDA(At, 0, 0); PG8_STAGE(PG8_SA(1, 1), gA, a1 + hstepA, voffA);
;             PG8_WAIT_L(8); PG8_BAR; PG8_WAIT_L(0); PG8_MMA(0, 0, At, B0); PG8_BAR; PG8_SCHED;
;             PG8_LDB(B1, 0, 1); PG8_STAGE(PG8_SB(0, 0), gB, b2, voffB);
;             PG8_BAR; PG8_WAIT_L(0); PG8_MMA(0, 1, At, B1); PG8_BAR;
;             PG8_LDA(At, 0, 1); PG8_STAGE(PG8_SA(0, 0), gA, a2, voffA);
;             PG8_BAR; PG8_WAIT_L(0); PG8_MMA(1, 0, At, B0); PG8_BAR; PG8_SCHED;
;             PG8_STAGE(PG8_SB(0, 1), gB, b2 + hstepB, voffB);
;             PG8_WAIT_V(6); PG8_BAR; PG8_MMA(1, 1, At, B1); PG8_BAR;
.LBB0_62:
	s_add_i32 s16, s6, s14
	s_addk_i32 s16, 0x100
	s_add_i32 s17, s7, s14
	s_cmpk_eq_i32 s14, 0x700
	s_cselect_b32 s55, s45, s16
	s_cselect_b32 s54, s52, s17
	s_add_i32 s17, 0, 0x10000
	v_add_u32_e32 v146, s17, v201
	ds_read_b128 v[134:137], v146
	ds_read_b128 v[138:141], v146 offset:1024
	ds_read_b128 v[142:145], v146 offset:2048
	ds_read_b128 v[146:149], v146 offset:3072
	s_or_b32 s16, s55, 0x80
	v_lshl_add_u64 v[202:203], v[130:131], 0, s[14:15]
	s_add_i32 m0, s23, 0xc000
	ds_read_b128 v[150:153], v205
	ds_read_b128 v[174:177], v205 offset:1024
	ds_read_b128 v[178:181], v205 offset:2048
	ds_read_b128 v[182:185], v205 offset:3072
	ds_read_b128 v[186:189], v205 offset:4096
	ds_read_b128 v[190:193], v205 offset:5120
	ds_read_b128 v[194:197], v205 offset:6144
	ds_read_b128 v[206:209], v205 offset:7168
	global_load_lds_dwordx4 v[202:203], off
	v_lshl_add_u64 v[202:203], v[132:133], 0, s[14:15]
	s_add_i32 m0, s23, 0xe000
	s_nop 0
	global_load_lds_dwordx4 v[202:203], off
	s_waitcnt lgkmcnt(8)
	s_barrier
	s_waitcnt lgkmcnt(0)
	s_setprio 1
	s_waitcnt lgkmcnt(0)
	v_mfma_f32_16x16x32_bf16 v[126:129], v[134:137], v[150:153], v[126:129]
	v_mfma_f32_16x16x32_bf16 v[118:121], v[142:145], v[150:153], v[118:121]
	v_mfma_f32_16x16x32_bf16 v[110:113], v[134:137], v[178:181], v[110:113]
	v_mfma_f32_16x16x32_bf16 v[102:105], v[142:145], v[178:181], v[102:105]
	v_mfma_f32_16x16x32_bf16 v[94:97], v[134:137], v[186:189], v[94:97]
	v_mfma_f32_16x16x32_bf16 v[86:89], v[142:145], v[186:189], v[86:89]
	v_mfma_f32_16x16x32_bf16 v[78:81], v[134:137], v[194:197], v[78:81]
	v_mfma_f32_16x16x32_bf16 v[70:73], v[142:145], v[194:197], v[70:73]
	v_mfma_f32_16x16x32_bf16 v[126:129], v[138:141], v[174:177], v[126:129]
	v_mfma_f32_16x16x32_bf16 v[118:121], v[146:149], v[174:177], v[118:121]
	v_mfma_f32_16x16x32_bf16 v[110:113], v[138:141], v[182:185], v[110:113]
	v_mfma_f32_16x16x32_bf16 v[102:105], v[146:149], v[182:185], v[102:105]
	v_mfma_f32_16x16x32_bf16 v[94:97], v[138:141], v[190:193], v[94:97]
	v_mfma_f32_16x16x32_bf16 v[86:89], v[146:149], v[190:193], v[86:89]
	v_mfma_f32_16x16x32_bf16 v[78:81], v[138:141], v[206:209], v[78:81]
	v_mfma_f32_16x16x32_bf16 v[70:73], v[146:149], v[206:209], v[70:73]
	s_setprio 0
	s_barrier
	s_add_i32 s62, 0, 0x14000
	s_add_u32 s72, s10, s54
	s_addc_u32 s73, s11, 0
	s_add_i32 s17, s17, s21
	v_add_u32_e32 v198, s62, v201
	v_lshl_add_u64 v[202:203], s[72:73], 0, v[0:1]
	s_mov_b32 m0, s17
	ds_read_b128 v[210:213], v198
	ds_read_b128 v[214:217], v198 offset:1024
	ds_read_b128 v[218:221], v198 offset:2048
	ds_read_b128 v[222:225], v198 offset:3072
	global_load_lds_dwordx4 v[202:203], off
	v_lshl_add_u64 v[202:203], s[72:73], 0, v[154:155]
	s_add_i32 m0, s17, 0x2000
	s_nop 0
	global_load_lds_dwordx4 v[202:203], off
	s_barrier
	s_waitcnt lgkmcnt(0)
	s_setprio 1
	s_waitcnt lgkmcnt(0)
	v_mfma_f32_16x16x32_bf16 v[122:125], v[210:213], v[150:153], v[122:125]
	v_mfma_f32_16x16x32_bf16 v[114:117], v[218:221], v[150:153], v[114:117]
	v_mfma_f32_16x16x32_bf16 v[106:109], v[210:213], v[178:181], v[106:109]
	v_mfma_f32_16x16x32_bf16 v[98:101], v[218:221], v[178:181], v[98:101]
	v_mfma_f32_16x16x32_bf16 v[90:93], v[210:213], v[186:189], v[90:93]
	v_mfma_f32_16x16x32_bf16 v[82:85], v[218:221], v[186:189], v[82:85]
	v_mfma_f32_16x16x32_bf16 v[74:77], v[210:213], v[194:197], v[74:77]
	v_mfma_f32_16x16x32_bf16 v[66:69], v[218:221], v[194:197], v[66:69]
	v_mfma_f32_16x16x32_bf16 v[122:125], v[214:217], v[174:177], v[122:125]
	v_mfma_f32_16x16x32_bf16 v[114:117], v[222:225], v[174:177], v[114:117]
	v_mfma_f32_16x16x32_bf16 v[106:109], v[214:217], v[182:185], v[106:109]
	v_mfma_f32_16x16x32_bf16 v[98:101], v[222:225], v[182:185], v[98:101]
	v_mfma_f32_16x16x32_bf16 v[90:93], v[214:217], v[190:193], v[90:93]
	v_mfma_f32_16x16x32_bf16 v[82:85], v[222:225], v[190:193], v[82:85]
	v_mfma_f32_16x16x32_bf16 v[74:77], v[214:217], v[206:209], v[74:77]
	v_mfma_f32_16x16x32_bf16 v[66:69], v[222:225], v[206:209], v[66:69]
	s_setprio 0
	s_add_u32 s72, s8, s55
	s_addc_u32 s73, s9, 0
	s_mov_b32 m0, s23
	v_lshl_add_u64 v[202:203], s[72:73], 0, v[158:159]
	s_barrier
	ds_read_b128 v[150:153], v205 offset:16384
	ds_read_b128 v[174:177], v205 offset:17408
	ds_read_b128 v[178:181], v205 offset:18432
	ds_read_b128 v[182:185], v205 offset:19456
	ds_read_b128 v[186:189], v205 offset:20480
	ds_read_b128 v[190:193], v205 offset:21504
	ds_read_b128 v[194:197], v205 offset:22528
	ds_read_b128 v[206:209], v205 offset:23552
	global_load_lds_dwordx4 v[202:203], off
	v_lshl_add_u64 v[202:203], s[72:73], 0, v[156:157]
	s_mov_b32 m0, s24
	s_nop 0
	global_load_lds_dwordx4 v[202:203], off
	s_barrier
	s_waitcnt lgkmcnt(0)
	s_setprio 1
	s_waitcnt lgkmcnt(0)
	v_mfma_f32_16x16x32_bf16 v[62:65], v[134:137], v[150:153], v[62:65]
	v_mfma_f32_16x16x32_bf16 v[54:57], v[142:145], v[150:153], v[54:57]
	v_mfma_f32_16x16x32_bf16 v[46:49], v[134:137], v[178:181], v[46:49]
	v_mfma_f32_16x16x32_bf16 v[38:41], v[142:145], v[178:181], v[38:41]
	v_mfma_f32_16x16x32_bf16 v[30:33], v[134:137], v[186:189], v[30:33]
	v_mfma_f32_16x16x32_bf16 v[22:25], v[142:145], v[186:189], v[22:25]
	v_mfma_f32_16x16x32_bf16 v[14:17], v[134:137], v[194:197], v[14:17]
	v_mfma_f32_16x16x32_bf16 v[6:9], v[142:145], v[194:197], v[6:9]
	v_mfma_f32_16x16x32_bf16 v[62:65], v[138:141], v[174:177], v[62:65]
	v_mfma_f32_16x16x32_bf16 v[54:57], v[146:149], v[174:177], v[54:57]
	v_mfma_f32_16x16x32_bf16 v[46:49], v[138:141], v[182:185], v[46:49]
	v_mfma_f32_16x16x32_bf16 v[38:41], v[146:149], v[182:185], v[38:41]
	v_mfma_f32_16x16x32_bf16 v[30:33], v[138:141], v[190:193], v[30:33]
	v_mfma_f32_16x16x32_bf16 v[22:25], v[146:149], v[190:193], v[22:25]
	v_mfma_f32_16x16x32_bf16 v[14:17], v[138:141], v[206:209], v[14:17]
	v_mfma_f32_16x16x32_bf16 v[6:9], v[146:149], v[206:209], v[6:9]
	s_setprio 0
	s_barrier
	s_add_i32 s17, s54, 0x40000
	s_add_u32 s72, s10, s17
	s_addc_u32 s73, s11, 0
	s_add_i32 s17, s62, s21
	v_lshl_add_u64 v[134:135], s[72:73], 0, v[0:1]
	s_mov_b32 m0, s17
	s_nop 0
	global_load_lds_dwordx4 v[134:135], off
	v_lshl_add_u64 v[134:135], s[72:73], 0, v[154:155]
	s_add_i32 m0, s17, 0x2000
	s_nop 0
	global_load_lds_dwordx4 v[134:135], off
	s_waitcnt vmcnt(6)
	s_barrier
	s_cmp_lg_u32 s53, -2
	s_cbranch_scc1 .Lrs_skip_a
	s_lshl_b32 s46, s44, 14
	s_add_u32 s46, s46, s92
	s_addc_u32 s47, s93, 0
	s_add_u32 s46, s46, 0x300000
	s_addc_u32 s47, s47, 0
	s_add_u32 s48, s46, 0x2000
	s_addc_u32 s49, s47, 0
	v_lshlrev_b32_e32 v226, 4, v232
	s_add_i32 m0, s23, 0x22000
	s_nop 0
	global_load_lds_dwordx4 v226, s[46:47]
	s_add_i32 m0, s23, 0x24000
	s_nop 0
	global_load_lds_dwordx4 v226, s[48:49]
; #define PG8_STAGE(bufoff, gbase, soff, voff) do { _Pragma("unroll") for (int _i = 0; _i < 2; ++_i) \
;         __builtin_amdgcn_global_load_lds((const unsigned*)(((gbase) + (size_t)(unsigned)(soff)) + (voff)[_i]), (LAS unsigned*)(lds + (bufoff) + ldsw + _i * 8192), 16, 0, 0); } while (0)
; #define PG8_LDA(dst, b, h) do { _Pragma("unroll") for (int m = 0; m < 4; ++m) _Pragma("unroll") for (int k = 0; k < 2; ++k) dst[m][k] = *(const LAS bf16x8*)(lds + PG8_SA(b, h) + aoff + m * 2048 + k * 1024); } while (0)
; #define PG8_LDB(dst, b, h) do { _Pragma("unroll") for (int n = 0; n < 2; ++n) _Pragma("unroll") for (int k = 0; k < 2; ++k) dst[n][k] = *(const LAS bf16x8*)(lds + PG8_SB(b, h) + boff + n * 2048 + k * 1024); } while (0)
; #define PG8_MMA(ai, bj, At, Bt) do { __builtin_amdgcn_s_setprio(1); _Pragma("unroll") for (int m = 0; m < 4; ++m) _Pragma("unroll") for (int n = 0; n < 2; ++n) _Pragma("unroll") for (int k = 0; k < 2; ++k) \
;         acc[ai][bj][m][n] = __builtin_amdgcn_mfma_f32_16x16x32_bf16(Bt[n][k], At[m][k], acc[ai][bj][m][n], 0, 0, 0); __builtin_amdgcn_s_setprio(0); } while (0)
; #define PG8_WAIT_V(n) asm volatile("s_waitcnt vmcnt(" #n ")" ::: "memory")
; #define PG8_WAIT_L(n) asm volatile("s_waitcnt lgkmcnt(" #n ")" ::: "memory")
; #define PG8_BAR __builtin_amdgcn_s_barrier()
; #define PG8_SCHED __builtin_amdgcn_sched_barrier(0)
; template <class Epi>
; __device__ __forceinline__ void gemm_phase(LAS unsigned char* lds, const Gemm g, const StaticOrder& S, const Epi& E, const int tid) {
;     ...
;             PG8_WAIT_V(6); PG8_BAR; PG8_MMA(1, 1, At, B1); PG8_BAR;
;             PG8_LDB(B0, 1, 0); PG8_SCHED; PG8_LDA(At, 1, 0); PG8_STAGE(PG8_SA(0, 1), gA, a2 + hstepA, voffA);
;             PG8_WAIT_L(8); PG8_BAR; PG8_WAIT_L(0); PG8_MMA(0, 0, At, B0); PG8_BAR; PG8_SCHED;
;             PG8_LDB(B1, 1, 1); PG8_STAGE(PG8_SB(1, 0), gB, b3, voffB);
;             PG8_BAR; PG8_WAIT_L(0); PG8_MMA(0, 1, At, B1); PG8_BAR;
;             PG8_LDA(At, 1, 1); PG8_STAGE(PG8_SA(1, 0), gA, a3, voffA);
;             PG8_BAR; PG8_WAIT_L(0); PG8_MMA(1, 0, At, B0); PG8_BAR; PG8_SCHED;
.Lrs_skip_a:
	s_setprio 1
	v_mfma_f32_16x16x32_bf16 v[58:61], v[210:213], v[150:153], v[58:61]
	v_mfma_f32_16x16x32_bf16 v[50:53], v[218:221], v[150:153], v[50:53]
	v_mfma_f32_16x16x32_bf16 v[42:45], v[210:213], v[178:181], v[42:45]
	v_mfma_f32_16x16x32_bf16 v[34:37], v[218:221], v[178:181], v[34:37]
	v_mfma_f32_16x16x32_bf16 v[26:29], v[210:213], v[186:189], v[26:29]
	v_mfma_f32_16x16x32_bf16 v[18:21], v[218:221], v[186:189], v[18:21]
	v_mfma_f32_16x16x32_bf16 v[10:13], v[210:213], v[194:197], v[10:13]
	v_mfma_f32_16x16x32_bf16 v[2:5], v[218:221], v[194:197], v[2:5]
	v_mfma_f32_16x16x32_bf16 v[58:61], v[214:217], v[174:177], v[58:61]
	v_mfma_f32_16x16x32_bf16 v[50:53], v[222:225], v[174:177], v[50:53]
	v_mfma_f32_16x16x32_bf16 v[42:45], v[214:217], v[182:185], v[42:45]
	v_mfma_f32_16x16x32_bf16 v[34:37], v[222:225], v[182:185], v[34:37]
	v_mfma_f32_16x16x32_bf16 v[26:29], v[214:217], v[190:193], v[26:29]
	v_mfma_f32_16x16x32_bf16 v[18:21], v[222:225], v[190:193], v[18:21]
	v_mfma_f32_16x16x32_bf16 v[10:13], v[214:217], v[206:209], v[10:13]
	v_mfma_f32_16x16x32_bf16 v[2:5], v[222:225], v[206:209], v[2:5]
	s_setprio 0
	s_add_i32 s17, 0, 0x18000
	v_add_u32_e32 v146, s17, v201
	s_barrier
	ds_read_b128 v[134:137], v146
	ds_read_b128 v[138:141], v146 offset:1024
	ds_read_b128 v[142:145], v146 offset:2048
	ds_read_b128 v[146:149], v146 offset:3072
	s_add_i32 s55, s55, 0x40000
	s_add_u32 s72, s8, s55
	s_addc_u32 s73, s9, 0
	s_mov_b32 m0, s25
	v_lshl_add_u64 v[202:203], s[72:73], 0, v[158:159]
	ds_read_b128 v[150:153], v205 offset:32768
	ds_read_b128 v[174:177], v205 offset:33792
	ds_read_b128 v[178:181], v205 offset:34816
	ds_read_b128 v[182:185], v205 offset:35840
	ds_read_b128 v[186:189], v205 offset:36864
	ds_read_b128 v[190:193], v205 offset:37888
	ds_read_b128 v[194:197], v205 offset:38912
	ds_read_b128 v[206:209], v205 offset:39936
	global_load_lds_dwordx4 v[202:203], off
	v_lshl_add_u64 v[202:203], s[72:73], 0, v[156:157]
	s_mov_b32 m0, s26
	s_nop 0
	global_load_lds_dwordx4 v[202:203], off
	s_waitcnt lgkmcnt(8)
	s_barrier
	s_waitcnt lgkmcnt(0)
	s_setprio 1
	s_waitcnt lgkmcnt(0)
	v_mfma_f32_16x16x32_bf16 v[126:129], v[134:137], v[150:153], v[126:129]
	v_mfma_f32_16x16x32_bf16 v[118:121], v[142:145], v[150:153], v[118:121]
	v_mfma_f32_16x16x32_bf16 v[110:113], v[134:137], v[178:181], v[110:113]
	v_mfma_f32_16x16x32_bf16 v[102:105], v[142:145], v[178:181], v[102:105]
	v_mfma_f32_16x16x32_bf16 v[94:97], v[134:137], v[186:189], v[94:97]
	v_mfma_f32_16x16x32_bf16 v[86:89], v[142:145], v[186:189], v[86:89]
	v_mfma_f32_16x16x32_bf16 v[78:81], v[134:137], v[194:197], v[78:81]
	v_mfma_f32_16x16x32_bf16 v[70:73], v[142:145], v[194:197], v[70:73]
	v_mfma_f32_16x16x32_bf16 v[126:129], v[138:141], v[174:177], v[126:129]
	v_mfma_f32_16x16x32_bf16 v[118:121], v[146:149], v[174:177], v[118:121]
	v_mfma_f32_16x16x32_bf16 v[110:113], v[138:141], v[182:185], v[110:113]
	v_mfma_f32_16x16x32_bf16 v[102:105], v[146:149], v[182:185], v[102:105]
	v_mfma_f32_16x16x32_bf16 v[94:97], v[138:141], v[190:193], v[94:97]
	v_mfma_f32_16x16x32_bf16 v[86:89], v[146:149], v[190:193], v[86:89]
	v_mfma_f32_16x16x32_bf16 v[78:81], v[138:141], v[206:209], v[78:81]
	v_mfma_f32_16x16x32_bf16 v[70:73], v[146:149], v[206:209], v[70:73]
	s_setprio 0
	s_barrier
	s_add_i32 s55, 0, 0x1c000
	s_or_b32 s62, s54, 0x80
	s_add_i32 s17, s17, s21
	v_add_u32_e32 v198, s55, v201
	v_lshl_add_u64 v[202:203], v[160:161], 0, s[62:63]
	s_mov_b32 m0, s17
	ds_read_b128 v[210:213], v198
	ds_read_b128 v[214:217], v198 offset:1024
	ds_read_b128 v[218:221], v198 offset:2048
	ds_read_b128 v[222:225], v198 offset:3072
	global_load_lds_dwordx4 v[202:203], off
	v_lshl_add_u64 v[202:203], v[162:163], 0, s[62:63]
	s_add_i32 m0, s17, 0x2000
	s_nop 0
	global_load_lds_dwordx4 v[202:203], off
	s_barrier
	s_waitcnt lgkmcnt(0)
	s_setprio 1
	s_waitcnt lgkmcnt(0)
	v_mfma_f32_16x16x32_bf16 v[122:125], v[210:213], v[150:153], v[122:125]
	v_mfma_f32_16x16x32_bf16 v[114:117], v[218:221], v[150:153], v[114:117]
	v_mfma_f32_16x16x32_bf16 v[106:109], v[210:213], v[178:181], v[106:109]
	v_mfma_f32_16x16x32_bf16 v[98:101], v[218:221], v[178:181], v[98:101]
	v_mfma_f32_16x16x32_bf16 v[90:93], v[210:213], v[186:189], v[90:93]
	v_mfma_f32_16x16x32_bf16 v[82:85], v[218:221], v[186:189], v[82:85]
	v_mfma_f32_16x16x32_bf16 v[74:77], v[210:213], v[194:197], v[74:77]
	v_mfma_f32_16x16x32_bf16 v[66:69], v[218:221], v[194:197], v[66:69]
	v_mfma_f32_16x16x32_bf16 v[122:125], v[214:217], v[174:177], v[122:125]
	v_mfma_f32_16x16x32_bf16 v[114:117], v[222:225], v[174:177], v[114:117]
	v_mfma_f32_16x16x32_bf16 v[106:109], v[214:217], v[182:185], v[106:109]
	v_mfma_f32_16x16x32_bf16 v[98:101], v[222:225], v[182:185], v[98:101]
	v_mfma_f32_16x16x32_bf16 v[90:93], v[214:217], v[190:193], v[90:93]
	v_mfma_f32_16x16x32_bf16 v[82:85], v[222:225], v[190:193], v[82:85]
	v_mfma_f32_16x16x32_bf16 v[74:77], v[214:217], v[206:209], v[74:77]
	v_mfma_f32_16x16x32_bf16 v[66:69], v[222:225], v[206:209], v[66:69]
	s_setprio 0
	s_mov_b32 s17, s63
	s_mov_b32 m0, s27
	v_lshl_add_u64 v[202:203], v[164:165], 0, s[16:17]
	s_barrier
	ds_read_b128 v[150:153], v205 offset:49152
	ds_read_b128 v[174:177], v205 offset:50176
	ds_read_b128 v[178:181], v205 offset:51200
	ds_read_b128 v[182:185], v205 offset:52224
	ds_read_b128 v[186:189], v205 offset:53248
	ds_read_b128 v[190:193], v205 offset:54272
	ds_read_b128 v[194:197], v205 offset:55296
	ds_read_b128 v[206:209], v205 offset:56320
	global_load_lds_dwordx4 v[202:203], off
	v_lshl_add_u64 v[202:203], v[166:167], 0, s[16:17]
	s_mov_b32 m0, s28
	s_nop 0
	global_load_lds_dwordx4 v[202:203], off
	s_barrier
; #define PG8_STAGE(bufoff, gbase, soff, voff) do { _Pragma("unroll") for (int _i = 0; _i < 2; ++_i) \
;         __builtin_amdgcn_global_load_lds((const unsigned*)(((gbase) + (size_t)(unsigned)(soff)) + (voff)[_i]), (LAS unsigned*)(lds + (bufoff) + ldsw + _i * 8192), 16, 0, 0); } while (0)
; #define PG8_MMA(ai, bj, At, Bt) do { __builtin_amdgcn_s_setprio(1); _Pragma("unroll") for (int m = 0; m < 4; ++m) _Pragma("unroll") for (int n = 0; n < 2; ++n) _Pragma("unroll") for (int k = 0; k < 2; ++k) \
;         acc[ai][bj][m][n] = __builtin_amdgcn_mfma_f32_16x16x32_bf16(Bt[n][k], At[m][k], acc[ai][bj][m][n], 0, 0, 0); __builtin_amdgcn_s_setprio(0); } while (0)
; #define PG8_WAIT_V(n) asm volatile("s_waitcnt vmcnt(" #n ")" ::: "memory")
; #define PG8_WAIT_L(n) asm volatile("s_waitcnt lgkmcnt(" #n ")" ::: "memory")
; #define PG8_BAR __builtin_amdgcn_s_barrier()
; #define PG8_SCHED __builtin_amdgcn_sched_barrier(0)
; __device__ __forceinline__ void rstd8(float (&rs)[2][4], const float* ssp, int row0, int fq) {
;     f32x4 p[2][4];
; #pragma unroll
;     for (int ai = 0; ai < 2; ++ai)
; #pragma unroll
;         for (int m = 0; m < 4; ++m) p[ai][m] = *(const f32x4*)(ssp + (size_t)(row0 + ai * 128 + m * 16) * 16 + fq * 4);
; template <class Epi>
; __device__ __forceinline__ void gemm_phase(LAS unsigned char* lds, const Gemm g, const StaticOrder& S, const Epi& E, const int tid) {
;     ...
;             PG8_BAR; PG8_WAIT_L(0); PG8_MMA(1, 0, At, B0); PG8_BAR; PG8_SCHED;
;             PG8_STAGE(PG8_SB(1, 1), gB, b3 + hstepB, voffB);
;             PG8_WAIT_V(6); PG8_BAR; PG8_MMA(1, 1, At, B1); PG8_BAR;
;         }
;         E(acc, cur, wr, wc, fr, fq);
	s_waitcnt lgkmcnt(0)
	s_setprio 1
	s_waitcnt lgkmcnt(0)
	v_mfma_f32_16x16x32_bf16 v[62:65], v[134:137], v[150:153], v[62:65]
	v_mfma_f32_16x16x32_bf16 v[54:57], v[142:145], v[150:153], v[54:57]
	v_mfma_f32_16x16x32_bf16 v[46:49], v[134:137], v[178:181], v[46:49]
	v_mfma_f32_16x16x32_bf16 v[38:41], v[142:145], v[178:181], v[38:41]
	v_mfma_f32_16x16x32_bf16 v[30:33], v[134:137], v[186:189], v[30:33]
	v_mfma_f32_16x16x32_bf16 v[22:25], v[142:145], v[186:189], v[22:25]
	v_mfma_f32_16x16x32_bf16 v[14:17], v[134:137], v[194:197], v[14:17]
	v_mfma_f32_16x16x32_bf16 v[6:9], v[142:145], v[194:197], v[6:9]
	v_mfma_f32_16x16x32_bf16 v[62:65], v[138:141], v[174:177], v[62:65]
	v_mfma_f32_16x16x32_bf16 v[54:57], v[146:149], v[174:177], v[54:57]
	v_mfma_f32_16x16x32_bf16 v[46:49], v[138:141], v[182:185], v[46:49]
	v_mfma_f32_16x16x32_bf16 v[38:41], v[146:149], v[182:185], v[38:41]
	v_mfma_f32_16x16x32_bf16 v[30:33], v[138:141], v[190:193], v[30:33]
	v_mfma_f32_16x16x32_bf16 v[22:25], v[146:149], v[190:193], v[22:25]
	v_mfma_f32_16x16x32_bf16 v[14:17], v[138:141], v[206:209], v[14:17]
	v_mfma_f32_16x16x32_bf16 v[6:9], v[146:149], v[206:209], v[6:9]
	s_setprio 0
	s_barrier
	s_add_i32 s54, s54, 0x40080
	s_add_u32 s16, s10, s54
	s_addc_u32 s17, s11, 0
	s_add_i32 s54, s55, s21
	v_lshl_add_u64 v[134:135], s[16:17], 0, v[0:1]
	s_mov_b32 m0, s54
	s_nop 0
	global_load_lds_dwordx4 v[134:135], off
	v_lshl_add_u64 v[134:135], s[16:17], 0, v[154:155]
	s_add_i32 m0, s54, 0x2000
	s_nop 0
	global_load_lds_dwordx4 v[134:135], off
	s_waitcnt vmcnt(6)
	s_barrier
	s_setprio 1
	v_mfma_f32_16x16x32_bf16 v[58:61], v[210:213], v[150:153], v[58:61]
	v_mfma_f32_16x16x32_bf16 v[50:53], v[218:221], v[150:153], v[50:53]
	v_mfma_f32_16x16x32_bf16 v[42:45], v[210:213], v[178:181], v[42:45]
	v_mfma_f32_16x16x32_bf16 v[34:37], v[218:221], v[178:181], v[34:37]
	v_mfma_f32_16x16x32_bf16 v[26:29], v[210:213], v[186:189], v[26:29]
	v_mfma_f32_16x16x32_bf16 v[18:21], v[218:221], v[186:189], v[18:21]
	v_mfma_f32_16x16x32_bf16 v[10:13], v[210:213], v[194:197], v[10:13]
	v_mfma_f32_16x16x32_bf16 v[2:5], v[218:221], v[194:197], v[2:5]
	v_mfma_f32_16x16x32_bf16 v[58:61], v[214:217], v[174:177], v[58:61]
	v_mfma_f32_16x16x32_bf16 v[50:53], v[222:225], v[174:177], v[50:53]
	v_mfma_f32_16x16x32_bf16 v[42:45], v[214:217], v[182:185], v[42:45]
	v_mfma_f32_16x16x32_bf16 v[34:37], v[222:225], v[182:185], v[34:37]
	v_mfma_f32_16x16x32_bf16 v[26:29], v[214:217], v[190:193], v[26:29]
	v_mfma_f32_16x16x32_bf16 v[18:21], v[222:225], v[190:193], v[18:21]
	v_mfma_f32_16x16x32_bf16 v[10:13], v[214:217], v[206:209], v[10:13]
	v_mfma_f32_16x16x32_bf16 v[2:5], v[222:225], v[206:209], v[2:5]
	s_setprio 0
	s_add_i32 s53, s53, 2
	s_add_u32 s14, s14, 0x100
	s_addc_u32 s15, s15, 0
	s_cmp_gt_u32 s53, 13
	s_barrier
	s_cbranch_scc0 .LBB0_62
	v_bfe_u32 v227, v232, 4, 2
	v_lshlrev_b32_e32 v227, 4, v227
	v_lshl_add_u32 v227, v199, 6, v227
	v_add_u32_e32 v227, 0x22000, v227
	v_lshl_add_u32 v196, s44, 8, v199
	v_ashrrev_i32_e32 v197, 31, v196
	v_lshlrev_b64 v[130:131], 6, v[196:197]
	v_or_b32_e32 v194, 16, v196
	v_lshl_add_u64 v[130:131], v[168:169], 0, v[130:131]
	v_ashrrev_i32_e32 v195, 31, v194
	ds_read_b128 v[186:189], v227 offset:0
	v_lshlrev_b64 v[130:131], 6, v[194:195]
	v_lshl_add_u64 v[130:131], v[168:169], 0, v[130:131]
	ds_read_b128 v[190:193], v227 offset:1024
	v_or_b32_e32 v184, 32, v196
	v_ashrrev_i32_e32 v185, 31, v184
	v_lshlrev_b64 v[130:131], 6, v[184:185]
	v_or_b32_e32 v182, 48, v196
	v_lshl_add_u64 v[130:131], v[168:169], 0, v[130:131]
	v_ashrrev_i32_e32 v183, 31, v182
	ds_read_b128 v[150:153], v227 offset:2048
	v_lshlrev_b64 v[130:131], 6, v[182:183]
	v_lshl_add_u64 v[130:131], v[168:169], 0, v[130:131]
	ds_read_b128 v[146:149], v227 offset:3072
	v_add_u32_e32 v180, 0x80, v196
	v_ashrrev_i32_e32 v181, 31, v180
	v_lshlrev_b64 v[130:131], 6, v[180:181]
	v_add_u32_e32 v178, 0x90, v196
	v_lshl_add_u64 v[130:131], v[168:169], 0, v[130:131]
	v_ashrrev_i32_e32 v179, 31, v178
	ds_read_b128 v[142:145], v227 offset:8192
	v_lshlrev_b64 v[130:131], 6, v[178:179]
	v_lshl_add_u64 v[130:131], v[168:169], 0, v[130:131]
	ds_read_b128 v[138:141], v227 offset:9216
	v_add_u32_e32 v176, 0xa0, v196
	v_ashrrev_i32_e32 v177, 31, v176
	v_lshlrev_b64 v[130:131], 6, v[176:177]
	v_add_u32_e32 v174, 0xb0, v196
	v_lshl_add_u64 v[130:131], v[168:169], 0, v[130:131]
	v_ashrrev_i32_e32 v175, 31, v174
	ds_read_b128 v[134:137], v227 offset:10240
	v_lshlrev_b64 v[130:131], 6, v[174:175]
	v_lshl_add_u64 v[130:131], v[168:169], 0, v[130:131]
	ds_read_b128 v[130:133], v227 offset:11264
	v_and_b32_e32 v177, 64, v237
	v_xor_b32_e32 v175, 16, v237
	v_add_u32_e32 v179, 64, v177
	v_cmp_lt_i32_e32 vcc, v175, v179
	s_mov_b32 s6, 0x358637bd
	s_mov_b32 s44, s34
	v_cndmask_b32_e32 v175, v237, v175, vcc
	v_lshlrev_b32_e32 v177, 2, v175
	v_xor_b32_e32 v175, 32, v237
	v_cmp_lt_i32_e32 vcc, v175, v179
	s_mov_b32 s16, s38
	s_waitcnt lgkmcnt(0)
	v_mov_b32_e32 v202, v187
	v_mov_b32_e32 v203, v188
	v_mov_b32_e32 v187, v189
	v_mov_b32_e32 v188, v191
	v_mov_b32_e32 v189, v192
	v_mov_b32_e32 v191, v193
	v_pk_add_f32 v[186:187], v[202:203], v[186:187]
	v_pk_add_f32 v[188:189], v[188:189], v[190:191]
	v_mov_b32_e32 v191, v186
	v_mov_b32_e32 v190, v188
	v_mov_b32_e32 v186, v189
	v_pk_add_f32 v[186:187], v[190:191], v[186:187]
	ds_bpermute_b32 v189, v177, v187
	ds_bpermute_b32 v188, v177, v186
	v_cndmask_b32_e32 v175, v237, v175, vcc
	v_lshlrev_b32_e32 v175, 2, v175
	v_mov_b64_e32 v[202:203], s[6:7]
	s_waitcnt lgkmcnt(0)
	v_pk_add_f32 v[186:187], v[186:187], v[188:189]
	ds_bpermute_b32 v189, v175, v187
	ds_bpermute_b32 v188, v175, v186
	s_waitcnt lgkmcnt(0)
; __device__ __forceinline__ float sigmoidf_(float x) { return __builtin_amdgcn_rcpf(1.0f + __expf(-x)); }
; __device__ __forceinline__ void rstd8(float (&rs)[2][4], const float* ssp, int row0, int fq) {
;     ...
;         for (int m = 0; m < 4; ++m) p[ai][m] = *(const f32x4*)(ssp + (size_t)(row0 + ai * 128 + m * 16) * 16 + fq * 4);
; #pragma unroll
;     for (int ai = 0; ai < 2; ++ai)
; #pragma unroll
;         for (int m = 0; m < 4; ++m) { float t = (p[ai][m][0] + p[ai][m][1]) + (p[ai][m][2] + p[ai][m][3]); t += __shfl_xor(t, 16); t += __shfl_xor(t, 32); rs[ai][m] = rsqrtf(t * (1.0f / 1024.0f) + 1e-6f); }
;     __device__ __forceinline__ void operator()(const Acc& acc, const Unit& u, int wr, int wc, int fr, int fq) const {
;     ...
;             for (int m = 0; m < 4; ++m) { const int row = row0 + ai * 128 + m * 16; const float rs = rs8[ai][m]; f32x4 h[2];
; #pragma unroll
;                 for (int n = 0; n < 2; ++n) { const f32x4 gt = acc[ai][0][m][n] * rs, up = acc[ai][1][m][n] * rs;
; #pragma unroll
;                     for (int jj = 0; jj < 4; ++jj) h[n][jj] = gt[jj] * sigmoidf_(gt[jj]) * up[jj]; }
	v_pk_add_f32 v[186:187], v[186:187], v[188:189]
	s_nop 0
	v_pk_fma_f32 v[186:187], v[186:187], s[70:71], v[202:203] op_sel_hi:[1,0,0]
	s_nop 0
	v_mul_f32_e32 v179, 0x4b800000, v187
	v_cmp_gt_f32_e64 s[6:7], s76, v187
	v_cmp_gt_f32_e32 vcc, s76, v186
	s_nop 0
	v_cndmask_b32_e64 v179, v187, v179, s[6:7]
	v_rsq_f32_e32 v179, v179
	v_mov_b32_e32 v187, v152
	v_mov_b32_e32 v152, v147
	v_mov_b32_e32 v147, v149
	v_mul_f32_e32 v181, 0x45800000, v179
	v_cndmask_b32_e64 v200, v179, v181, s[6:7]
	v_mul_f32_e32 v179, 0x4b800000, v186
	v_cndmask_b32_e32 v179, v186, v179, vcc
	v_mov_b32_e32 v186, v151
	v_mov_b32_e32 v151, v153
	v_mov_b32_e32 v153, v148
	v_pk_add_f32 v[150:151], v[186:187], v[150:151]
	v_pk_add_f32 v[146:147], v[152:153], v[146:147]
	v_mov_b32_e32 v149, v150
	v_mov_b32_e32 v148, v146
	v_mov_b32_e32 v150, v147
	v_pk_add_f32 v[146:147], v[148:149], v[150:151]
	ds_bpermute_b32 v149, v177, v147
	ds_bpermute_b32 v148, v177, v146
	v_mov_b32_e32 v150, v143
	v_mov_b32_e32 v151, v144
	v_mov_b32_e32 v143, v145
	v_mov_b32_e32 v144, v139
	v_mov_b32_e32 v145, v140
	v_mov_b32_e32 v139, v141
	v_pk_add_f32 v[142:143], v[150:151], v[142:143]
	v_pk_add_f32 v[138:139], v[144:145], v[138:139]
	s_waitcnt lgkmcnt(0)
	v_pk_add_f32 v[146:147], v[146:147], v[148:149]
	v_mov_b32_e32 v140, v138
	v_mov_b32_e32 v141, v142
	v_mov_b32_e32 v142, v139
	ds_bpermute_b32 v149, v175, v147
	ds_bpermute_b32 v148, v175, v146
	v_pk_add_f32 v[138:139], v[140:141], v[142:143]
	ds_bpermute_b32 v141, v177, v139
	ds_bpermute_b32 v140, v177, v138
	v_mov_b32_e32 v142, v135
	v_mov_b32_e32 v143, v136
	v_mov_b32_e32 v135, v137
	v_mov_b32_e32 v136, v131
	v_mov_b32_e32 v137, v132
	v_mov_b32_e32 v131, v133
	s_waitcnt lgkmcnt(2)
	v_pk_add_f32 v[146:147], v[146:147], v[148:149]
	v_pk_add_f32 v[134:135], v[142:143], v[134:135]
	v_pk_add_f32 v[130:131], v[136:137], v[130:131]
	v_pk_fma_f32 v[146:147], v[146:147], s[70:71], v[202:203] op_sel_hi:[1,0,0]
	s_waitcnt lgkmcnt(0)
	v_pk_add_f32 v[138:139], v[138:139], v[140:141]
	v_mov_b32_e32 v132, v130
	v_mov_b32_e32 v133, v134
	v_mov_b32_e32 v134, v131
	v_mul_f32_e32 v148, 0x4b800000, v147
	v_cmp_gt_f32_e64 s[6:7], s76, v147
	ds_bpermute_b32 v141, v175, v139
	ds_bpermute_b32 v140, v175, v138
	v_pk_add_f32 v[130:131], v[132:133], v[134:135]
	v_cndmask_b32_e64 v147, v147, v148, s[6:7]
	ds_bpermute_b32 v133, v177, v131
	ds_bpermute_b32 v132, v177, v130
	v_rsq_f32_e32 v179, v179
	v_rsq_f32_e32 v147, v147
	s_waitcnt lgkmcnt(2)
	v_pk_add_f32 v[138:139], v[138:139], v[140:141]
	v_pk_mul_f32 v[126:127], v[126:127], v[200:201] op_sel_hi:[1,0]
	v_mul_f32_e32 v181, 0x45800000, v179
	v_mul_f32_e32 v148, 0x45800000, v147
	v_pk_fma_f32 v[138:139], v[138:139], s[70:71], v[202:203] op_sel_hi:[1,0,0]
	s_waitcnt lgkmcnt(0)
	v_pk_add_f32 v[130:131], v[130:131], v[132:133]
	v_cndmask_b32_e32 v198, v179, v181, vcc
	v_cmp_gt_f32_e32 vcc, s76, v146
	v_cndmask_b32_e64 v148, v147, v148, s[6:7]
	v_mul_f32_e32 v147, 0x4b800000, v146
	v_mul_f32_e32 v140, 0x4b800000, v139
	v_cmp_gt_f32_e64 s[6:7], s76, v139
	ds_bpermute_b32 v133, v175, v131
	ds_bpermute_b32 v132, v175, v130
	v_cndmask_b32_e32 v146, v146, v147, vcc
	v_cndmask_b32_e64 v139, v139, v140, s[6:7]
	v_rsq_f32_e32 v146, v146
	v_rsq_f32_e32 v139, v139
	s_waitcnt lgkmcnt(0)
	v_pk_add_f32 v[130:131], v[130:131], v[132:133]
	v_pk_mul_f32 v[122:123], v[122:123], v[200:201] op_sel_hi:[1,0]
	v_mul_f32_e32 v147, 0x45800000, v146
	v_mul_f32_e32 v140, 0x45800000, v139
	v_pk_fma_f32 v[130:131], v[130:131], s[70:71], v[202:203] op_sel_hi:[1,0,0]
	v_cndmask_b32_e32 v146, v146, v147, vcc
	v_cmp_gt_f32_e32 vcc, s76, v138
	v_cndmask_b32_e64 v140, v139, v140, s[6:7]
	v_mul_f32_e32 v139, 0x4b800000, v138
	v_mul_f32_e32 v132, 0x4b800000, v131
	v_cmp_gt_f32_e64 s[6:7], s76, v131
	v_cndmask_b32_e32 v138, v138, v139, vcc
	v_rsq_f32_e32 v138, v138
	v_cndmask_b32_e64 v131, v131, v132, s[6:7]
	v_rsq_f32_e32 v131, v131
	v_pk_mul_f32 v[124:125], v[124:125], v[200:201] op_sel_hi:[1,0]
	v_mul_f32_e32 v139, 0x45800000, v138
	v_cndmask_b32_e32 v138, v138, v139, vcc
	v_mul_f32_e32 v132, 0x45800000, v131
	v_cmp_gt_f32_e32 vcc, s76, v130
	v_cndmask_b32_e64 v132, v131, v132, s[6:7]
	v_mul_f32_e32 v131, 0x4b800000, v130
	v_cndmask_b32_e32 v130, v130, v131, vcc
	v_rsq_f32_e32 v130, v130
	v_pk_mul_f32 v[118:119], v[118:119], v[200:201] op_sel_hi:[1,0]
	v_pk_mul_f32 v[114:115], v[114:115], v[200:201] op_sel_hi:[1,0]
	v_lshl_or_b32 v134, s39, 7, v204
	v_mul_f32_e32 v131, 0x45800000, v130
	v_cndmask_b32_e32 v130, v130, v131, vcc
	v_mul_f32_e32 v131, 0xbfb8aa3b, v126
	v_exp_f32_e32 v131, v131
	v_pk_mul_f32 v[116:117], v[116:117], v[200:201] op_sel_hi:[1,0]
	v_ashrrev_i32_e32 v135, 31, v134
	v_pk_mul_f32 v[110:111], v[110:111], v[198:199] op_sel_hi:[1,0]
	v_add_f32_e32 v131, 1.0, v131
	v_rcp_f32_e32 v136, v131
	v_mul_f32_e32 v131, 0xbfb8aa3b, v127
	v_exp_f32_e32 v131, v131
	v_pk_mul_f32 v[106:107], v[106:107], v[198:199] op_sel_hi:[1,0]
	v_pk_mul_f32 v[108:109], v[108:109], v[198:199] op_sel_hi:[1,0]
	v_pk_mul_f32 v[102:103], v[102:103], v[198:199] op_sel_hi:[1,0]
	v_add_f32_e32 v131, 1.0, v131
	v_rcp_f32_e32 v137, v131
	v_pk_mul_f32 v[98:99], v[98:99], v[198:199] op_sel_hi:[1,0]
	v_pk_mul_f32 v[100:101], v[100:101], v[198:199] op_sel_hi:[1,0]
	v_pk_mul_f32 v[94:95], v[94:95], v[148:149] op_sel_hi:[1,0]
	v_pk_mul_f32 v[126:127], v[126:127], v[136:137]
	v_pk_mul_f32 v[90:91], v[90:91], v[148:149] op_sel_hi:[1,0]
	v_pk_mul_f32 v[122:123], v[122:123], v[126:127]
	v_pk_mul_f32 v[126:127], v[128:129], v[200:201] op_sel_hi:[1,0]
	v_pk_mul_f32 v[92:93], v[92:93], v[148:149] op_sel_hi:[1,0]
	v_mul_f32_e32 v128, 0xbfb8aa3b, v126
	v_mul_f32_e32 v129, 0xbfb8aa3b, v127
; __device__ __forceinline__ unsigned cvt_pk_bf16(float lo, float hi) { const f32x2 v = {lo, hi}; const bf16x2_t r = __builtin_convertvector(v, bf16x2_t); return __builtin_bit_cast(unsigned, r); }
; __device__ __forceinline__ float sigmoidf_(float x) { return __builtin_amdgcn_rcpf(1.0f + __expf(-x)); }
;     __device__ __forceinline__ void operator()(const Acc& acc, const Unit& u, int wr, int wc, int fr, int fq) const {
;     ...
;             for (int m = 0; m < 4; ++m) { const int row = row0 + ai * 128 + m * 16; const float rs = rs8[ai][m]; f32x4 h[2];
; #pragma unroll
;                 for (int n = 0; n < 2; ++n) { const f32x4 gt = acc[ai][0][m][n] * rs, up = acc[ai][1][m][n] * rs;
; #pragma unroll
;                     for (int jj = 0; jj < 4; ++jj) h[n][jj] = gt[jj] * sigmoidf_(gt[jj]) * up[jj]; }
;                 u32x4 w; w.x = cvt_pk_bf16(h[0][0], h[0][1]); w.y = cvt_pk_bf16(h[0][2], h[0][3]); w.z = cvt_pk_bf16(h[1][0], h[1][1]); w.w = cvt_pk_bf16(h[1][2], h[1][3]);
;                 *(u32x4*)(H + (size_t)row * FF + hc0) = w; }
	v_exp_f32_e32 v128, v128
	v_exp_f32_e32 v129, v129
	v_pk_mul_f32 v[86:87], v[86:87], v[148:149] op_sel_hi:[1,0]
	v_pk_mul_f32 v[82:83], v[82:83], v[148:149] op_sel_hi:[1,0]
	v_add_f32_e32 v128, 1.0, v128
	v_add_f32_e32 v129, 1.0, v129
	v_rcp_f32_e32 v128, v128
	v_rcp_f32_e32 v129, v129
	v_pk_mul_f32 v[84:85], v[84:85], v[148:149] op_sel_hi:[1,0]
	v_pk_mul_f32 v[78:79], v[78:79], v[146:147] op_sel_hi:[1,0]
	v_pk_mul_f32 v[74:75], v[74:75], v[146:147] op_sel_hi:[1,0]
	v_pk_mul_f32 v[126:127], v[126:127], v[128:129]
	v_pk_mul_f32 v[76:77], v[76:77], v[146:147] op_sel_hi:[1,0]
	v_pk_mul_f32 v[124:125], v[124:125], v[126:127]
	v_mul_f32_e32 v126, 0xbfb8aa3b, v118
	v_mul_f32_e32 v127, 0xbfb8aa3b, v119
	v_exp_f32_e32 v126, v126
	v_exp_f32_e32 v127, v127
	v_pk_mul_f32 v[70:71], v[70:71], v[146:147] op_sel_hi:[1,0]
	v_pk_mul_f32 v[66:67], v[66:67], v[146:147] op_sel_hi:[1,0]
	v_add_f32_e32 v126, 1.0, v126
	v_add_f32_e32 v127, 1.0, v127
	v_rcp_f32_e32 v126, v126
	v_rcp_f32_e32 v127, v127
	v_pk_mul_f32 v[68:69], v[68:69], v[146:147] op_sel_hi:[1,0]
	v_pk_mul_f32 v[62:63], v[62:63], v[140:141] op_sel_hi:[1,0]
	v_pk_mul_f32 v[58:59], v[58:59], v[140:141] op_sel_hi:[1,0]
	v_pk_mul_f32 v[118:119], v[118:119], v[126:127]
	v_pk_mul_f32 v[60:61], v[60:61], v[140:141] op_sel_hi:[1,0]
	v_pk_mul_f32 v[114:115], v[114:115], v[118:119]
	v_pk_mul_f32 v[118:119], v[120:121], v[200:201] op_sel_hi:[1,0]
	v_pk_mul_f32 v[54:55], v[54:55], v[140:141] op_sel_hi:[1,0]
	v_mul_f32_e32 v120, 0xbfb8aa3b, v118
	v_mul_f32_e32 v121, 0xbfb8aa3b, v119
	v_exp_f32_e32 v120, v120
	v_exp_f32_e32 v121, v121
	v_pk_mul_f32 v[50:51], v[50:51], v[140:141] op_sel_hi:[1,0]
	v_pk_mul_f32 v[52:53], v[52:53], v[140:141] op_sel_hi:[1,0]
	v_add_f32_e32 v120, 1.0, v120
	v_add_f32_e32 v121, 1.0, v121
	v_rcp_f32_e32 v120, v120
	v_rcp_f32_e32 v121, v121
	v_pk_mul_f32 v[46:47], v[46:47], v[138:139] op_sel_hi:[1,0]
	v_pk_mul_f32 v[42:43], v[42:43], v[138:139] op_sel_hi:[1,0]
	v_pk_mul_f32 v[44:45], v[44:45], v[138:139] op_sel_hi:[1,0]
	v_pk_mul_f32 v[118:119], v[118:119], v[120:121]
	v_cvt_pk_bf16_f32 v120, v114, v115
	v_pk_mul_f32 v[116:117], v[116:117], v[118:119]
	v_mov_b64_e32 v[114:115], s[12:13]
	v_cvt_pk_bf16_f32 v118, v122, v123
	v_cvt_pk_bf16_f32 v121, v116, v117
	v_mad_i64_i32 v[122:123], s[6:7], v196, s78, v[114:115]
	v_lshlrev_b64 v[116:117], 1, v[134:135]
	v_cvt_pk_bf16_f32 v119, v124, v125
	v_lshl_add_u64 v[122:123], v[122:123], 0, v[116:117]
	global_store_dwordx4 v[122:123], v[118:121], off
	v_pk_mul_f32 v[38:39], v[38:39], v[138:139] op_sel_hi:[1,0]
	v_pk_mul_f32 v[34:35], v[34:35], v[138:139] op_sel_hi:[1,0]
	v_mul_f32_e32 v118, 0xbfb8aa3b, v110
	v_mul_f32_e32 v119, 0xbfb8aa3b, v111
	v_exp_f32_e32 v118, v118
	v_exp_f32_e32 v119, v119
	v_pk_mul_f32 v[36:37], v[36:37], v[138:139] op_sel_hi:[1,0]
	v_pk_mul_f32 v[30:31], v[30:31], v[132:133] op_sel_hi:[1,0]
	v_add_f32_e32 v118, 1.0, v118
	v_add_f32_e32 v119, 1.0, v119
	v_rcp_f32_e32 v118, v118
	v_rcp_f32_e32 v119, v119
	v_pk_mul_f32 v[26:27], v[26:27], v[132:133] op_sel_hi:[1,0]
	v_pk_mul_f32 v[28:29], v[28:29], v[132:133] op_sel_hi:[1,0]
	v_pk_mul_f32 v[22:23], v[22:23], v[132:133] op_sel_hi:[1,0]
	v_pk_mul_f32 v[110:111], v[110:111], v[118:119]
	v_pk_mul_f32 v[18:19], v[18:19], v[132:133] op_sel_hi:[1,0]
	v_pk_mul_f32 v[106:107], v[106:107], v[110:111]
	v_pk_mul_f32 v[110:111], v[112:113], v[198:199] op_sel_hi:[1,0]
	v_pk_mul_f32 v[20:21], v[20:21], v[132:133] op_sel_hi:[1,0]
	v_mul_f32_e32 v112, 0xbfb8aa3b, v110
	v_mul_f32_e32 v113, 0xbfb8aa3b, v111
	v_exp_f32_e32 v112, v112
	v_exp_f32_e32 v113, v113
	v_pk_mul_f32 v[14:15], v[14:15], v[130:131] op_sel_hi:[1,0]
	v_pk_mul_f32 v[10:11], v[10:11], v[130:131] op_sel_hi:[1,0]
	v_add_f32_e32 v112, 1.0, v112
	v_add_f32_e32 v113, 1.0, v113
	v_rcp_f32_e32 v112, v112
	v_rcp_f32_e32 v113, v113
	v_pk_mul_f32 v[12:13], v[12:13], v[130:131] op_sel_hi:[1,0]
	v_pk_mul_f32 v[6:7], v[6:7], v[130:131] op_sel_hi:[1,0]
	v_pk_mul_f32 v[2:3], v[2:3], v[130:131] op_sel_hi:[1,0]
	v_pk_mul_f32 v[110:111], v[110:111], v[112:113]
	v_pk_mul_f32 v[4:5], v[4:5], v[130:131] op_sel_hi:[1,0]
	v_pk_mul_f32 v[108:109], v[108:109], v[110:111]
	v_mul_f32_e32 v110, 0xbfb8aa3b, v102
	v_mul_f32_e32 v111, 0xbfb8aa3b, v103
	v_exp_f32_e32 v110, v110
	v_exp_f32_e32 v111, v111
	s_and_b64 vcc, exec, s[4:5]
	s_mov_b32 s39, s31
	v_add_f32_e32 v110, 1.0, v110
	v_add_f32_e32 v111, 1.0, v111
	v_rcp_f32_e32 v110, v110
	v_rcp_f32_e32 v111, v111
	s_nop 0
	v_pk_mul_f32 v[102:103], v[102:103], v[110:111]
	s_nop 0
	v_pk_mul_f32 v[102:103], v[98:99], v[102:103]
	v_pk_mul_f32 v[98:99], v[104:105], v[198:199] op_sel_hi:[1,0]
	s_nop 0
	v_mul_f32_e32 v104, 0xbfb8aa3b, v98
	v_mul_f32_e32 v105, 0xbfb8aa3b, v99
	v_exp_f32_e32 v104, v104
	v_exp_f32_e32 v105, v105
	v_add_f32_e32 v104, 1.0, v104
	v_add_f32_e32 v105, 1.0, v105
	v_rcp_f32_e32 v104, v104
	v_rcp_f32_e32 v105, v105
	s_nop 0
	v_pk_mul_f32 v[98:99], v[98:99], v[104:105]
	s_nop 0
	v_pk_mul_f32 v[104:105], v[100:101], v[98:99]
	v_cvt_pk_bf16_f32 v100, v102, v103
	v_mad_i64_i32 v[102:103], s[6:7], v194, s78, v[114:115]
	v_cvt_pk_bf16_f32 v98, v106, v107
	v_cvt_pk_bf16_f32 v99, v108, v109
	v_cvt_pk_bf16_f32 v101, v104, v105
	v_lshl_add_u64 v[102:103], v[102:103], 0, v[116:117]
	global_store_dwordx4 v[102:103], v[98:101], off
	s_nop 1
	v_mul_f32_e32 v98, 0xbfb8aa3b, v94
	v_mul_f32_e32 v99, 0xbfb8aa3b, v95
	v_exp_f32_e32 v98, v98
	v_exp_f32_e32 v99, v99
	v_add_f32_e32 v98, 1.0, v98
	v_add_f32_e32 v99, 1.0, v99
	v_rcp_f32_e32 v98, v98
	v_rcp_f32_e32 v99, v99
	s_nop 0
	v_pk_mul_f32 v[94:95], v[94:95], v[98:99]
	s_nop 0
	v_pk_mul_f32 v[90:91], v[90:91], v[94:95]
	v_pk_mul_f32 v[94:95], v[96:97], v[148:149] op_sel_hi:[1,0]
; __device__ __forceinline__ unsigned cvt_pk_bf16(float lo, float hi) { const f32x2 v = {lo, hi}; const bf16x2_t r = __builtin_convertvector(v, bf16x2_t); return __builtin_bit_cast(unsigned, r); }
; __device__ __forceinline__ float sigmoidf_(float x) { return __builtin_amdgcn_rcpf(1.0f + __expf(-x)); }
;     __device__ __forceinline__ void operator()(const Acc& acc, const Unit& u, int wr, int wc, int fr, int fq) const {
;     ...
;                 for (int n = 0; n < 2; ++n) { const f32x4 gt = acc[ai][0][m][n] * rs, up = acc[ai][1][m][n] * rs;
; #pragma unroll
;                     for (int jj = 0; jj < 4; ++jj) h[n][jj] = gt[jj] * sigmoidf_(gt[jj]) * up[jj]; }
;                 u32x4 w; w.x = cvt_pk_bf16(h[0][0], h[0][1]); w.y = cvt_pk_bf16(h[0][2], h[0][3]); w.z = cvt_pk_bf16(h[1][0], h[1][1]); w.w = cvt_pk_bf16(h[1][2], h[1][3]);
;                 *(u32x4*)(H + (size_t)row * FF + hc0) = w; }
	s_nop 0
	v_mul_f32_e32 v96, 0xbfb8aa3b, v94
	v_mul_f32_e32 v97, 0xbfb8aa3b, v95
	v_exp_f32_e32 v96, v96
	v_exp_f32_e32 v97, v97
	v_add_f32_e32 v96, 1.0, v96
	v_add_f32_e32 v97, 1.0, v97
	v_rcp_f32_e32 v96, v96
	v_rcp_f32_e32 v97, v97
	s_nop 0
	v_pk_mul_f32 v[94:95], v[94:95], v[96:97]
	s_nop 0
	v_pk_mul_f32 v[92:93], v[92:93], v[94:95]
	v_mul_f32_e32 v94, 0xbfb8aa3b, v86
	v_mul_f32_e32 v95, 0xbfb8aa3b, v87
	v_exp_f32_e32 v94, v94
	v_exp_f32_e32 v95, v95
	v_add_f32_e32 v94, 1.0, v94
	v_add_f32_e32 v95, 1.0, v95
	v_rcp_f32_e32 v94, v94
	v_rcp_f32_e32 v95, v95
	s_nop 0
	v_pk_mul_f32 v[86:87], v[86:87], v[94:95]
	s_nop 0
	v_pk_mul_f32 v[86:87], v[82:83], v[86:87]
	v_pk_mul_f32 v[82:83], v[88:89], v[148:149] op_sel_hi:[1,0]
	s_nop 0
	v_mul_f32_e32 v88, 0xbfb8aa3b, v82
	v_mul_f32_e32 v89, 0xbfb8aa3b, v83
	v_exp_f32_e32 v88, v88
	v_exp_f32_e32 v89, v89
	v_add_f32_e32 v88, 1.0, v88
	v_add_f32_e32 v89, 1.0, v89
	v_rcp_f32_e32 v88, v88
	v_rcp_f32_e32 v89, v89
	s_nop 0
	v_pk_mul_f32 v[82:83], v[82:83], v[88:89]
	s_nop 0
	v_pk_mul_f32 v[88:89], v[84:85], v[82:83]
	v_cvt_pk_bf16_f32 v84, v86, v87
	v_mad_i64_i32 v[86:87], s[6:7], v184, s78, v[114:115]
	v_cvt_pk_bf16_f32 v82, v90, v91
	v_cvt_pk_bf16_f32 v83, v92, v93
	v_cvt_pk_bf16_f32 v85, v88, v89
	v_lshl_add_u64 v[86:87], v[86:87], 0, v[116:117]
	global_store_dwordx4 v[86:87], v[82:85], off
	s_nop 1
	v_mul_f32_e32 v82, 0xbfb8aa3b, v78
	v_mul_f32_e32 v83, 0xbfb8aa3b, v79
	v_exp_f32_e32 v82, v82
	v_exp_f32_e32 v83, v83
	v_add_f32_e32 v82, 1.0, v82
	v_add_f32_e32 v83, 1.0, v83
	v_rcp_f32_e32 v82, v82
	v_rcp_f32_e32 v83, v83
	s_nop 0
	v_pk_mul_f32 v[78:79], v[78:79], v[82:83]
	s_nop 0
	v_pk_mul_f32 v[74:75], v[74:75], v[78:79]
	v_pk_mul_f32 v[78:79], v[80:81], v[146:147] op_sel_hi:[1,0]
	s_nop 0
	v_mul_f32_e32 v80, 0xbfb8aa3b, v78
	v_mul_f32_e32 v81, 0xbfb8aa3b, v79
	v_exp_f32_e32 v80, v80
	v_exp_f32_e32 v81, v81
	v_add_f32_e32 v80, 1.0, v80
	v_add_f32_e32 v81, 1.0, v81
	v_rcp_f32_e32 v80, v80
	v_rcp_f32_e32 v81, v81
	s_nop 0
	v_pk_mul_f32 v[78:79], v[78:79], v[80:81]
	s_nop 0
	v_pk_mul_f32 v[76:77], v[76:77], v[78:79]
	v_mul_f32_e32 v78, 0xbfb8aa3b, v70
	v_mul_f32_e32 v79, 0xbfb8aa3b, v71
	v_exp_f32_e32 v78, v78
	v_exp_f32_e32 v79, v79
	v_add_f32_e32 v78, 1.0, v78
	v_add_f32_e32 v79, 1.0, v79
	v_rcp_f32_e32 v78, v78
	v_rcp_f32_e32 v79, v79
	s_nop 0
	v_pk_mul_f32 v[70:71], v[70:71], v[78:79]
	s_nop 0
	v_pk_mul_f32 v[70:71], v[66:67], v[70:71]
	v_pk_mul_f32 v[66:67], v[72:73], v[146:147] op_sel_hi:[1,0]
	s_nop 0
	v_mul_f32_e32 v72, 0xbfb8aa3b, v66
	v_mul_f32_e32 v73, 0xbfb8aa3b, v67
	v_exp_f32_e32 v72, v72
	v_exp_f32_e32 v73, v73
	v_add_f32_e32 v72, 1.0, v72
	v_add_f32_e32 v73, 1.0, v73
	v_rcp_f32_e32 v72, v72
	v_rcp_f32_e32 v73, v73
	s_nop 0
	v_pk_mul_f32 v[66:67], v[66:67], v[72:73]
	s_nop 0
	v_pk_mul_f32 v[72:73], v[68:69], v[66:67]
	v_cvt_pk_bf16_f32 v68, v70, v71
	v_mad_i64_i32 v[70:71], s[6:7], v182, s78, v[114:115]
	v_cvt_pk_bf16_f32 v66, v74, v75
	v_cvt_pk_bf16_f32 v67, v76, v77
	v_cvt_pk_bf16_f32 v69, v72, v73
	v_lshl_add_u64 v[70:71], v[70:71], 0, v[116:117]
	global_store_dwordx4 v[70:71], v[66:69], off
	s_nop 1
	v_mul_f32_e32 v66, 0xbfb8aa3b, v62
	v_mul_f32_e32 v67, 0xbfb8aa3b, v63
	v_exp_f32_e32 v66, v66
	v_exp_f32_e32 v67, v67
	v_add_f32_e32 v66, 1.0, v66
	v_add_f32_e32 v67, 1.0, v67
	v_rcp_f32_e32 v66, v66
	v_rcp_f32_e32 v67, v67
	s_nop 0
	v_pk_mul_f32 v[62:63], v[62:63], v[66:67]
	s_nop 0
	v_pk_mul_f32 v[58:59], v[58:59], v[62:63]
	v_pk_mul_f32 v[62:63], v[64:65], v[140:141] op_sel_hi:[1,0]
	s_nop 0
	v_mul_f32_e32 v64, 0xbfb8aa3b, v62
	v_mul_f32_e32 v65, 0xbfb8aa3b, v63
	v_exp_f32_e32 v64, v64
	v_exp_f32_e32 v65, v65
	v_add_f32_e32 v64, 1.0, v64
	v_add_f32_e32 v65, 1.0, v65
	v_rcp_f32_e32 v64, v64
	v_rcp_f32_e32 v65, v65
	s_nop 0
	v_pk_mul_f32 v[62:63], v[62:63], v[64:65]
	s_nop 0
	v_pk_mul_f32 v[60:61], v[60:61], v[62:63]
	v_mul_f32_e32 v62, 0xbfb8aa3b, v54
	v_mul_f32_e32 v63, 0xbfb8aa3b, v55
	v_exp_f32_e32 v62, v62
	v_exp_f32_e32 v63, v63
	v_add_f32_e32 v62, 1.0, v62
	v_add_f32_e32 v63, 1.0, v63
	v_rcp_f32_e32 v62, v62
	v_rcp_f32_e32 v63, v63
	s_nop 0
	v_pk_mul_f32 v[54:55], v[54:55], v[62:63]
	s_nop 0
	v_pk_mul_f32 v[54:55], v[50:51], v[54:55]
	v_pk_mul_f32 v[50:51], v[56:57], v[140:141] op_sel_hi:[1,0]
	s_nop 0
	v_mul_f32_e32 v56, 0xbfb8aa3b, v50
	v_mul_f32_e32 v57, 0xbfb8aa3b, v51
	v_exp_f32_e32 v56, v56
	v_exp_f32_e32 v57, v57
	v_add_f32_e32 v56, 1.0, v56
	v_add_f32_e32 v57, 1.0, v57
	v_rcp_f32_e32 v56, v56
	v_rcp_f32_e32 v57, v57
	s_nop 0
	v_pk_mul_f32 v[50:51], v[50:51], v[56:57]
	s_nop 0
	v_pk_mul_f32 v[56:57], v[52:53], v[50:51]
	v_cvt_pk_bf16_f32 v52, v54, v55
	v_mad_i64_i32 v[54:55], s[6:7], v180, s78, v[114:115]
	v_cvt_pk_bf16_f32 v50, v58, v59
	v_cvt_pk_bf16_f32 v51, v60, v61
	v_cvt_pk_bf16_f32 v53, v56, v57
	v_lshl_add_u64 v[54:55], v[54:55], 0, v[116:117]
	global_store_dwordx4 v[54:55], v[50:53], off
	s_nop 1
	v_mul_f32_e32 v50, 0xbfb8aa3b, v46
	v_mul_f32_e32 v51, 0xbfb8aa3b, v47
	v_exp_f32_e32 v50, v50
	v_exp_f32_e32 v51, v51
	v_add_f32_e32 v50, 1.0, v50
	v_add_f32_e32 v51, 1.0, v51
	v_rcp_f32_e32 v50, v50
	v_rcp_f32_e32 v51, v51
; __device__ __forceinline__ unsigned cvt_pk_bf16(float lo, float hi) { const f32x2 v = {lo, hi}; const bf16x2_t r = __builtin_convertvector(v, bf16x2_t); return __builtin_bit_cast(unsigned, r); }
; __device__ __forceinline__ float sigmoidf_(float x) { return __builtin_amdgcn_rcpf(1.0f + __expf(-x)); }
; #define PG8_WAIT_V(n) asm volatile("s_waitcnt vmcnt(" #n ")" ::: "memory")
; #define PG8_BAR __builtin_amdgcn_s_barrier()
; template <class Epi>
; __device__ __forceinline__ void gemm_phase(LAS unsigned char* lds, const Gemm g, const StaticOrder& S, const Epi& E, const int tid) {
;     ...
;     PG8_WAIT_V(0);
;     if (wr == 0) PG8_BAR;
;     PG8_BAR;
;     __device__ __forceinline__ void operator()(const Acc& acc, const Unit& u, int wr, int wc, int fr, int fq) const {
;     ...
;                 for (int n = 0; n < 2; ++n) { const f32x4 gt = acc[ai][0][m][n] * rs, up = acc[ai][1][m][n] * rs;
; #pragma unroll
;                     for (int jj = 0; jj < 4; ++jj) h[n][jj] = gt[jj] * sigmoidf_(gt[jj]) * up[jj]; }
;                 u32x4 w; w.x = cvt_pk_bf16(h[0][0], h[0][1]); w.y = cvt_pk_bf16(h[0][2], h[0][3]); w.z = cvt_pk_bf16(h[1][0], h[1][1]); w.w = cvt_pk_bf16(h[1][2], h[1][3]);
;                 *(u32x4*)(H + (size_t)row * FF + hc0) = w; }
	s_nop 0
	v_pk_mul_f32 v[46:47], v[46:47], v[50:51]
	s_nop 0
	v_pk_mul_f32 v[42:43], v[42:43], v[46:47]
	v_pk_mul_f32 v[46:47], v[48:49], v[138:139] op_sel_hi:[1,0]
	s_nop 0
	v_mul_f32_e32 v48, 0xbfb8aa3b, v46
	v_mul_f32_e32 v49, 0xbfb8aa3b, v47
	v_exp_f32_e32 v48, v48
	v_exp_f32_e32 v49, v49
	v_add_f32_e32 v48, 1.0, v48
	v_add_f32_e32 v49, 1.0, v49
	v_rcp_f32_e32 v48, v48
	v_rcp_f32_e32 v49, v49
	s_nop 0
	v_pk_mul_f32 v[46:47], v[46:47], v[48:49]
	s_nop 0
	v_pk_mul_f32 v[44:45], v[44:45], v[46:47]
	v_mul_f32_e32 v46, 0xbfb8aa3b, v38
	v_mul_f32_e32 v47, 0xbfb8aa3b, v39
	v_exp_f32_e32 v46, v46
	v_exp_f32_e32 v47, v47
	v_add_f32_e32 v46, 1.0, v46
	v_add_f32_e32 v47, 1.0, v47
	v_rcp_f32_e32 v46, v46
	v_rcp_f32_e32 v47, v47
	s_nop 0
	v_pk_mul_f32 v[38:39], v[38:39], v[46:47]
	s_nop 0
	v_pk_mul_f32 v[38:39], v[34:35], v[38:39]
	v_pk_mul_f32 v[34:35], v[40:41], v[138:139] op_sel_hi:[1,0]
	s_nop 0
	v_mul_f32_e32 v40, 0xbfb8aa3b, v34
	v_mul_f32_e32 v41, 0xbfb8aa3b, v35
	v_exp_f32_e32 v40, v40
	v_exp_f32_e32 v41, v41
	v_add_f32_e32 v40, 1.0, v40
	v_add_f32_e32 v41, 1.0, v41
	v_rcp_f32_e32 v40, v40
	v_rcp_f32_e32 v41, v41
	s_nop 0
	v_pk_mul_f32 v[34:35], v[34:35], v[40:41]
	s_nop 0
	v_pk_mul_f32 v[40:41], v[36:37], v[34:35]
	v_cvt_pk_bf16_f32 v36, v38, v39
	v_mad_i64_i32 v[38:39], s[6:7], v178, s78, v[114:115]
	v_cvt_pk_bf16_f32 v34, v42, v43
	v_cvt_pk_bf16_f32 v35, v44, v45
	v_cvt_pk_bf16_f32 v37, v40, v41
	v_lshl_add_u64 v[38:39], v[38:39], 0, v[116:117]
	global_store_dwordx4 v[38:39], v[34:37], off
	s_nop 1
	v_mul_f32_e32 v34, 0xbfb8aa3b, v30
	v_mul_f32_e32 v35, 0xbfb8aa3b, v31
	v_exp_f32_e32 v34, v34
	v_exp_f32_e32 v35, v35
	v_add_f32_e32 v34, 1.0, v34
	v_add_f32_e32 v35, 1.0, v35
	v_rcp_f32_e32 v34, v34
	v_rcp_f32_e32 v35, v35
	s_nop 0
	v_pk_mul_f32 v[30:31], v[30:31], v[34:35]
	s_nop 0
	v_pk_mul_f32 v[26:27], v[26:27], v[30:31]
	v_pk_mul_f32 v[30:31], v[32:33], v[132:133] op_sel_hi:[1,0]
	s_nop 0
	v_mul_f32_e32 v32, 0xbfb8aa3b, v30
	v_mul_f32_e32 v33, 0xbfb8aa3b, v31
	v_exp_f32_e32 v32, v32
	v_exp_f32_e32 v33, v33
	v_add_f32_e32 v32, 1.0, v32
	v_add_f32_e32 v33, 1.0, v33
	v_rcp_f32_e32 v32, v32
	v_rcp_f32_e32 v33, v33
	s_nop 0
	v_pk_mul_f32 v[30:31], v[30:31], v[32:33]
	s_nop 0
	v_pk_mul_f32 v[28:29], v[28:29], v[30:31]
	v_mul_f32_e32 v30, 0xbfb8aa3b, v22
	v_mul_f32_e32 v31, 0xbfb8aa3b, v23
	v_exp_f32_e32 v30, v30
	v_exp_f32_e32 v31, v31
	v_add_f32_e32 v30, 1.0, v30
	v_add_f32_e32 v31, 1.0, v31
	v_rcp_f32_e32 v30, v30
	v_rcp_f32_e32 v31, v31
	s_nop 0
	v_pk_mul_f32 v[22:23], v[22:23], v[30:31]
	s_nop 0
	v_pk_mul_f32 v[22:23], v[18:19], v[22:23]
	v_pk_mul_f32 v[18:19], v[24:25], v[132:133] op_sel_hi:[1,0]
	s_nop 0
	v_mul_f32_e32 v24, 0xbfb8aa3b, v18
	v_mul_f32_e32 v25, 0xbfb8aa3b, v19
	v_exp_f32_e32 v24, v24
	v_exp_f32_e32 v25, v25
	v_add_f32_e32 v24, 1.0, v24
	v_add_f32_e32 v25, 1.0, v25
	v_rcp_f32_e32 v24, v24
	v_rcp_f32_e32 v25, v25
	s_nop 0
	v_pk_mul_f32 v[18:19], v[18:19], v[24:25]
	s_nop 0
	v_pk_mul_f32 v[24:25], v[20:21], v[18:19]
	v_cvt_pk_bf16_f32 v20, v22, v23
	v_mad_i64_i32 v[22:23], s[6:7], v176, s78, v[114:115]
	v_cvt_pk_bf16_f32 v18, v26, v27
	v_cvt_pk_bf16_f32 v19, v28, v29
	v_cvt_pk_bf16_f32 v21, v24, v25
	v_lshl_add_u64 v[22:23], v[22:23], 0, v[116:117]
	global_store_dwordx4 v[22:23], v[18:21], off
	s_nop 1
	v_mul_f32_e32 v18, 0xbfb8aa3b, v14
	v_mul_f32_e32 v19, 0xbfb8aa3b, v15
	v_exp_f32_e32 v18, v18
	v_exp_f32_e32 v19, v19
	v_add_f32_e32 v18, 1.0, v18
	v_add_f32_e32 v19, 1.0, v19
	v_rcp_f32_e32 v18, v18
	v_rcp_f32_e32 v19, v19
	s_nop 0
	v_pk_mul_f32 v[14:15], v[14:15], v[18:19]
	s_nop 0
	v_pk_mul_f32 v[10:11], v[10:11], v[14:15]
	v_pk_mul_f32 v[14:15], v[16:17], v[130:131] op_sel_hi:[1,0]
	s_nop 0
	v_mul_f32_e32 v16, 0xbfb8aa3b, v14
	v_mul_f32_e32 v17, 0xbfb8aa3b, v15
	v_exp_f32_e32 v16, v16
	v_exp_f32_e32 v17, v17
	v_add_f32_e32 v16, 1.0, v16
	v_add_f32_e32 v17, 1.0, v17
	v_rcp_f32_e32 v16, v16
	v_rcp_f32_e32 v17, v17
	s_nop 0
	v_pk_mul_f32 v[14:15], v[14:15], v[16:17]
	s_nop 0
	v_pk_mul_f32 v[12:13], v[12:13], v[14:15]
	v_mul_f32_e32 v14, 0xbfb8aa3b, v6
	v_mul_f32_e32 v15, 0xbfb8aa3b, v7
	v_exp_f32_e32 v14, v14
	v_exp_f32_e32 v15, v15
	v_add_f32_e32 v14, 1.0, v14
	v_add_f32_e32 v15, 1.0, v15
	v_rcp_f32_e32 v14, v14
	v_rcp_f32_e32 v15, v15
	s_nop 0
	v_pk_mul_f32 v[6:7], v[6:7], v[14:15]
	s_nop 0
	v_pk_mul_f32 v[6:7], v[2:3], v[6:7]
	v_pk_mul_f32 v[2:3], v[8:9], v[130:131] op_sel_hi:[1,0]
	s_nop 0
	v_mul_f32_e32 v8, 0xbfb8aa3b, v2
	v_mul_f32_e32 v9, 0xbfb8aa3b, v3
	v_exp_f32_e32 v8, v8
	v_exp_f32_e32 v9, v9
	v_add_f32_e32 v8, 1.0, v8
	v_add_f32_e32 v9, 1.0, v9
	v_rcp_f32_e32 v8, v8
	v_rcp_f32_e32 v9, v9
	s_nop 0
	v_pk_mul_f32 v[2:3], v[2:3], v[8:9]
	s_nop 0
	v_pk_mul_f32 v[8:9], v[4:5], v[2:3]
	v_cvt_pk_bf16_f32 v4, v6, v7
	v_mad_i64_i32 v[6:7], s[6:7], v174, s78, v[114:115]
	v_cvt_pk_bf16_f32 v2, v10, v11
	v_cvt_pk_bf16_f32 v3, v12, v13
	v_cvt_pk_bf16_f32 v5, v8, v9
	v_lshl_add_u64 v[6:7], v[6:7], 0, v[116:117]
	s_mov_b32 s6, s35
	global_store_dwordx4 v[6:7], v[2:5], off
	s_cbranch_vccz .LBB0_59
	s_waitcnt vmcnt(0)
	s_cmpk_gt_u32 s20, 0xff
	s_cbranch_scc1 .LBB0_66
	s_barrier

; #define PG8_STAGE(bufoff, gbase, soff, voff) do { _Pragma("unroll") for (int _i = 0; _i < 2; ++_i) \
;         __builtin_amdgcn_global_load_lds((const unsigned*)(((gbase) + (size_t)(unsigned)(soff)) + (voff)[_i]), (LAS unsigned*)(lds + (bufoff) + ldsw + _i * 8192), 16, 0, 0); } while (0)
; #define PG8_LDA(dst, b, h) do { _Pragma("unroll") for (int m = 0; m < 4; ++m) _Pragma("unroll") for (int k = 0; k < 2; ++k) dst[m][k] = *(const LAS bf16x8*)(lds + PG8_SA(b, h) + aoff + m * 2048 + k * 1024); } while (0)
; #define PG8_LDB(dst, b, h) do { _Pragma("unroll") for (int n = 0; n < 2; ++n) _Pragma("unroll") for (int k = 0; k < 2; ++k) dst[n][k] = *(const LAS bf16x8*)(lds + PG8_SB(b, h) + boff + n * 2048 + k * 1024); } while (0)
; #define PG8_MMA(ai, bj, At, Bt) do { __builtin_amdgcn_s_setprio(1); _Pragma("unroll") for (int m = 0; m < 4; ++m) _Pragma("unroll") for (int n = 0; n < 2; ++n) _Pragma("unroll") for (int k = 0; k < 2; ++k) \
;         acc[ai][bj][m][n] = __builtin_amdgcn_mfma_f32_16x16x32_bf16(Bt[n][k], At[m][k], acc[ai][bj][m][n], 0, 0, 0); __builtin_amdgcn_s_setprio(0); } while (0)
; #define PG8_WAIT_V(n) asm volatile("s_waitcnt vmcnt(" #n ")" ::: "memory")
; #define PG8_WAIT_L(n) asm volatile("s_waitcnt lgkmcnt(" #n ")" ::: "memory")
; template <class Epi>
; __device__ __forceinline__ void gemm_phase(LAS unsigned char* lds, const Gemm g, const StaticOrder& S, const Epi& E, const int tid) {
;     ...
;             const bool last = (t == nt - 2);
;             const unsigned a1 = cA + (unsigned)(t + 1) * kstep;
;             const unsigned a2 = last ? nA : cA + (unsigned)(t + 2) * kstep, b2 = last ? nB : cB + (unsigned)(t + 2) * kstep;
;             const unsigned a3 = a2 + kstep, b3 = b2 + kstep;
;             PG8_LDB(B0, 0, 0); PG8_SCHED; PG8_LDA(At, 0, 0); PG8_STAGE(PG8_SA(1, 1), gA, a1 + hstepA, voffA);
;             PG8_WAIT_L(8); PG8_BAR; PG8_WAIT_L(0); PG8_MMA(0, 0, At, B0); PG8_BAR; PG8_SCHED;
;             PG8_LDB(B1, 0, 1); PG8_STAGE(PG8_SB(0, 0), gB, b2, voffB);
;             PG8_BAR; PG8_WAIT_L(0); PG8_MMA(0, 1, At, B1); PG8_BAR;
;             PG8_LDA(At, 0, 1); PG8_STAGE(PG8_SA(0, 0), gA, a2, voffA);
;             PG8_BAR; PG8_WAIT_L(0); PG8_MMA(1, 0, At, B0); PG8_BAR; PG8_SCHED;
;             PG8_STAGE(PG8_SB(0, 1), gB, b2 + hstepB, voffB);
;             PG8_WAIT_V(6); PG8_BAR; PG8_MMA(1, 1, At, B1); PG8_BAR;
.LBB0_525:
	s_add_i32 s16, s6, s14
	s_addk_i32 s16, 0x100
	s_add_i32 s17, s7, s14
	s_cmpk_eq_i32 s14, 0x700
	s_cselect_b32 s55, s45, s16
	s_cselect_b32 s54, s52, s17
	s_add_i32 s17, 0, 0x10000
	v_add_u32_e32 v146, s17, v201
	ds_read_b128 v[134:137], v146
	ds_read_b128 v[138:141], v146 offset:1024
	ds_read_b128 v[142:145], v146 offset:2048
	ds_read_b128 v[146:149], v146 offset:3072
	s_or_b32 s16, s55, 0x80
	v_lshl_add_u64 v[186:187], v[130:131], 0, s[14:15]
	s_add_i32 m0, s23, 0xc000
	ds_read_b128 v[150:153], v205
	ds_read_b128 v[174:177], v205 offset:1024
	ds_read_b128 v[178:181], v205 offset:2048
	ds_read_b128 v[182:185], v205 offset:3072
	ds_read_b128 v[194:197], v205 offset:4096
	ds_read_b128 v[206:209], v205 offset:5120
	ds_read_b128 v[210:213], v205 offset:6144
	ds_read_b128 v[214:217], v205 offset:7168
	global_load_lds_dwordx4 v[186:187], off
	v_lshl_add_u64 v[186:187], v[132:133], 0, s[14:15]
	s_add_i32 m0, s23, 0xe000
	s_nop 0
	global_load_lds_dwordx4 v[186:187], off
	s_waitcnt lgkmcnt(8)
	s_barrier
	s_waitcnt lgkmcnt(0)
	s_setprio 1
	s_waitcnt lgkmcnt(0)
	v_mfma_f32_16x16x32_bf16 v[126:129], v[134:137], v[150:153], v[126:129]
	v_mfma_f32_16x16x32_bf16 v[118:121], v[142:145], v[150:153], v[118:121]
	v_mfma_f32_16x16x32_bf16 v[110:113], v[134:137], v[178:181], v[110:113]
	v_mfma_f32_16x16x32_bf16 v[102:105], v[142:145], v[178:181], v[102:105]
	v_mfma_f32_16x16x32_bf16 v[94:97], v[134:137], v[194:197], v[94:97]
	v_mfma_f32_16x16x32_bf16 v[86:89], v[142:145], v[194:197], v[86:89]
	v_mfma_f32_16x16x32_bf16 v[78:81], v[134:137], v[210:213], v[78:81]
	v_mfma_f32_16x16x32_bf16 v[70:73], v[142:145], v[210:213], v[70:73]
	v_mfma_f32_16x16x32_bf16 v[126:129], v[138:141], v[174:177], v[126:129]
	v_mfma_f32_16x16x32_bf16 v[118:121], v[146:149], v[174:177], v[118:121]
	v_mfma_f32_16x16x32_bf16 v[110:113], v[138:141], v[182:185], v[110:113]
	v_mfma_f32_16x16x32_bf16 v[102:105], v[146:149], v[182:185], v[102:105]
	v_mfma_f32_16x16x32_bf16 v[94:97], v[138:141], v[206:209], v[94:97]
	v_mfma_f32_16x16x32_bf16 v[86:89], v[146:149], v[206:209], v[86:89]
	v_mfma_f32_16x16x32_bf16 v[78:81], v[138:141], v[214:217], v[78:81]
	v_mfma_f32_16x16x32_bf16 v[70:73], v[146:149], v[214:217], v[70:73]
	s_setprio 0
	s_barrier
	s_add_i32 s62, 0, 0x14000
	s_add_u32 s72, s8, s54
	v_add_u32_e32 v186, s62, v201
	s_addc_u32 s73, s9, 0
	s_add_i32 s17, s17, s21
	ds_read_b128 v[218:221], v186
	ds_read_b128 v[222:225], v186 offset:1024
	ds_read_b128 v[226:229], v186 offset:2048
	ds_read_b128 v[244:247], v186 offset:3072
	v_lshl_add_u64 v[186:187], s[72:73], 0, v[0:1]
	s_mov_b32 m0, s17
	s_nop 0
	global_load_lds_dwordx4 v[186:187], off
	v_lshl_add_u64 v[186:187], s[72:73], 0, v[154:155]
	s_add_i32 m0, s17, 0x2000
	s_nop 0
	global_load_lds_dwordx4 v[186:187], off
	s_barrier
	s_waitcnt lgkmcnt(0)
	s_setprio 1
	s_waitcnt lgkmcnt(0)
	v_mfma_f32_16x16x32_bf16 v[122:125], v[218:221], v[150:153], v[122:125]
	v_mfma_f32_16x16x32_bf16 v[114:117], v[226:229], v[150:153], v[114:117]
	v_mfma_f32_16x16x32_bf16 v[106:109], v[218:221], v[178:181], v[106:109]
	v_mfma_f32_16x16x32_bf16 v[98:101], v[226:229], v[178:181], v[98:101]
	v_mfma_f32_16x16x32_bf16 v[90:93], v[218:221], v[194:197], v[90:93]
	v_mfma_f32_16x16x32_bf16 v[82:85], v[226:229], v[194:197], v[82:85]
	v_mfma_f32_16x16x32_bf16 v[74:77], v[218:221], v[210:213], v[74:77]
	v_mfma_f32_16x16x32_bf16 v[66:69], v[226:229], v[210:213], v[66:69]
	v_mfma_f32_16x16x32_bf16 v[122:125], v[222:225], v[174:177], v[122:125]
	v_mfma_f32_16x16x32_bf16 v[114:117], v[244:247], v[174:177], v[114:117]
	v_mfma_f32_16x16x32_bf16 v[106:109], v[222:225], v[182:185], v[106:109]
	v_mfma_f32_16x16x32_bf16 v[98:101], v[244:247], v[182:185], v[98:101]
	v_mfma_f32_16x16x32_bf16 v[90:93], v[222:225], v[206:209], v[90:93]
	v_mfma_f32_16x16x32_bf16 v[82:85], v[244:247], v[206:209], v[82:85]
	v_mfma_f32_16x16x32_bf16 v[74:77], v[222:225], v[214:217], v[74:77]
	v_mfma_f32_16x16x32_bf16 v[66:69], v[244:247], v[214:217], v[66:69]
	s_setprio 0
	s_add_u32 s72, s10, s55
	s_addc_u32 s73, s11, 0
	s_mov_b32 m0, s23
	v_lshl_add_u64 v[186:187], s[72:73], 0, v[158:159]
	s_barrier
	ds_read_b128 v[150:153], v205 offset:16384
	ds_read_b128 v[174:177], v205 offset:17408
	ds_read_b128 v[178:181], v205 offset:18432
	ds_read_b128 v[182:185], v205 offset:19456
	ds_read_b128 v[194:197], v205 offset:20480
	ds_read_b128 v[206:209], v205 offset:21504
	ds_read_b128 v[210:213], v205 offset:22528
	ds_read_b128 v[214:217], v205 offset:23552
	global_load_lds_dwordx4 v[186:187], off
	v_lshl_add_u64 v[186:187], s[72:73], 0, v[156:157]
	s_mov_b32 m0, s24
	s_nop 0
	global_load_lds_dwordx4 v[186:187], off
	s_barrier
	s_waitcnt lgkmcnt(0)
	s_setprio 1
	s_waitcnt lgkmcnt(0)
	v_mfma_f32_16x16x32_bf16 v[62:65], v[134:137], v[150:153], v[62:65]
	v_mfma_f32_16x16x32_bf16 v[54:57], v[142:145], v[150:153], v[54:57]
	v_mfma_f32_16x16x32_bf16 v[46:49], v[134:137], v[178:181], v[46:49]
	v_mfma_f32_16x16x32_bf16 v[38:41], v[142:145], v[178:181], v[38:41]
	v_mfma_f32_16x16x32_bf16 v[30:33], v[134:137], v[194:197], v[30:33]
	v_mfma_f32_16x16x32_bf16 v[22:25], v[142:145], v[194:197], v[22:25]
	v_mfma_f32_16x16x32_bf16 v[14:17], v[134:137], v[210:213], v[14:17]
	v_mfma_f32_16x16x32_bf16 v[6:9], v[142:145], v[210:213], v[6:9]
	v_mfma_f32_16x16x32_bf16 v[62:65], v[138:141], v[174:177], v[62:65]
	v_mfma_f32_16x16x32_bf16 v[54:57], v[146:149], v[174:177], v[54:57]
	v_mfma_f32_16x16x32_bf16 v[46:49], v[138:141], v[182:185], v[46:49]
	v_mfma_f32_16x16x32_bf16 v[38:41], v[146:149], v[182:185], v[38:41]
	v_mfma_f32_16x16x32_bf16 v[30:33], v[138:141], v[206:209], v[30:33]
	v_mfma_f32_16x16x32_bf16 v[22:25], v[146:149], v[206:209], v[22:25]
	v_mfma_f32_16x16x32_bf16 v[14:17], v[138:141], v[214:217], v[14:17]
	v_mfma_f32_16x16x32_bf16 v[6:9], v[146:149], v[214:217], v[6:9]
	s_setprio 0
	s_barrier
	s_add_i32 s17, s54, 0x40000
	s_add_u32 s72, s8, s17
	s_addc_u32 s73, s9, 0
	s_add_i32 s17, s62, s21
	v_lshl_add_u64 v[134:135], s[72:73], 0, v[0:1]
	s_mov_b32 m0, s17
	s_nop 0
	global_load_lds_dwordx4 v[134:135], off
	v_lshl_add_u64 v[134:135], s[72:73], 0, v[154:155]
	s_add_i32 m0, s17, 0x2000
	s_nop 0
	global_load_lds_dwordx4 v[134:135], off
	s_waitcnt vmcnt(6)
	s_barrier
	s_cmp_lg_u32 s53, -2
	s_cbranch_scc1 .Lrs_skip_b
	s_lshl_b32 s46, s44, 14
	s_add_u32 s46, s46, s92
	s_addc_u32 s47, s93, 0
	s_add_u32 s46, s46, 0x100000
	s_addc_u32 s47, s47, 0
	s_add_u32 s48, s46, 0x2000
	s_addc_u32 s49, s47, 0
	v_lshlrev_b32_e32 v192, 4, v232
	s_add_i32 m0, s23, 0x22000
	s_nop 0
	global_load_lds_dwordx4 v192, s[46:47]
	s_add_i32 m0, s23, 0x24000
	s_nop 0
	global_load_lds_dwordx4 v192, s[48:49]
; #define PG8_STAGE(bufoff, gbase, soff, voff) do { _Pragma("unroll") for (int _i = 0; _i < 2; ++_i) \
;         __builtin_amdgcn_global_load_lds((const unsigned*)(((gbase) + (size_t)(unsigned)(soff)) + (voff)[_i]), (LAS unsigned*)(lds + (bufoff) + ldsw + _i * 8192), 16, 0, 0); } while (0)
; #define PG8_LDA(dst, b, h) do { _Pragma("unroll") for (int m = 0; m < 4; ++m) _Pragma("unroll") for (int k = 0; k < 2; ++k) dst[m][k] = *(const LAS bf16x8*)(lds + PG8_SA(b, h) + aoff + m * 2048 + k * 1024); } while (0)
; #define PG8_LDB(dst, b, h) do { _Pragma("unroll") for (int n = 0; n < 2; ++n) _Pragma("unroll") for (int k = 0; k < 2; ++k) dst[n][k] = *(const LAS bf16x8*)(lds + PG8_SB(b, h) + boff + n * 2048 + k * 1024); } while (0)
; #define PG8_MMA(ai, bj, At, Bt) do { __builtin_amdgcn_s_setprio(1); _Pragma("unroll") for (int m = 0; m < 4; ++m) _Pragma("unroll") for (int n = 0; n < 2; ++n) _Pragma("unroll") for (int k = 0; k < 2; ++k) \
;         acc[ai][bj][m][n] = __builtin_amdgcn_mfma_f32_16x16x32_bf16(Bt[n][k], At[m][k], acc[ai][bj][m][n], 0, 0, 0); __builtin_amdgcn_s_setprio(0); } while (0)
; #define PG8_WAIT_V(n) asm volatile("s_waitcnt vmcnt(" #n ")" ::: "memory")
; #define PG8_WAIT_L(n) asm volatile("s_waitcnt lgkmcnt(" #n ")" ::: "memory")
; #define PG8_BAR __builtin_amdgcn_s_barrier()
; #define PG8_SCHED __builtin_amdgcn_sched_barrier(0)
; template <class Epi>
; __device__ __forceinline__ void gemm_phase(LAS unsigned char* lds, const Gemm g, const StaticOrder& S, const Epi& E, const int tid) {
;     ...
;             PG8_WAIT_V(6); PG8_BAR; PG8_MMA(1, 1, At, B1); PG8_BAR;
;             PG8_LDB(B0, 1, 0); PG8_SCHED; PG8_LDA(At, 1, 0); PG8_STAGE(PG8_SA(0, 1), gA, a2 + hstepA, voffA);
;             PG8_WAIT_L(8); PG8_BAR; PG8_WAIT_L(0); PG8_MMA(0, 0, At, B0); PG8_BAR; PG8_SCHED;
;             PG8_LDB(B1, 1, 1); PG8_STAGE(PG8_SB(1, 0), gB, b3, voffB);
;             PG8_BAR; PG8_WAIT_L(0); PG8_MMA(0, 1, At, B1); PG8_BAR;
;             PG8_LDA(At, 1, 1); PG8_STAGE(PG8_SA(1, 0), gA, a3, voffA);
.Lrs_skip_b:
	s_setprio 1
	v_mfma_f32_16x16x32_bf16 v[58:61], v[218:221], v[150:153], v[58:61]
	v_mfma_f32_16x16x32_bf16 v[50:53], v[226:229], v[150:153], v[50:53]
	v_mfma_f32_16x16x32_bf16 v[42:45], v[218:221], v[178:181], v[42:45]
	v_mfma_f32_16x16x32_bf16 v[34:37], v[226:229], v[178:181], v[34:37]
	v_mfma_f32_16x16x32_bf16 v[26:29], v[218:221], v[194:197], v[26:29]
	v_mfma_f32_16x16x32_bf16 v[18:21], v[226:229], v[194:197], v[18:21]
	v_mfma_f32_16x16x32_bf16 v[10:13], v[218:221], v[210:213], v[10:13]
	v_mfma_f32_16x16x32_bf16 v[2:5], v[226:229], v[210:213], v[2:5]
	v_mfma_f32_16x16x32_bf16 v[58:61], v[222:225], v[174:177], v[58:61]
	v_mfma_f32_16x16x32_bf16 v[50:53], v[244:247], v[174:177], v[50:53]
	v_mfma_f32_16x16x32_bf16 v[42:45], v[222:225], v[182:185], v[42:45]
	v_mfma_f32_16x16x32_bf16 v[34:37], v[244:247], v[182:185], v[34:37]
	v_mfma_f32_16x16x32_bf16 v[26:29], v[222:225], v[206:209], v[26:29]
	v_mfma_f32_16x16x32_bf16 v[18:21], v[244:247], v[206:209], v[18:21]
	v_mfma_f32_16x16x32_bf16 v[10:13], v[222:225], v[214:217], v[10:13]
	v_mfma_f32_16x16x32_bf16 v[2:5], v[244:247], v[214:217], v[2:5]
	s_setprio 0
	s_add_i32 s17, 0, 0x18000
	v_add_u32_e32 v146, s17, v201
	s_barrier
	ds_read_b128 v[134:137], v146
	ds_read_b128 v[138:141], v146 offset:1024
	ds_read_b128 v[142:145], v146 offset:2048
	ds_read_b128 v[146:149], v146 offset:3072
	s_add_i32 s55, s55, 0x40000
	s_add_u32 s72, s10, s55
	s_addc_u32 s73, s11, 0
	s_mov_b32 m0, s25
	v_lshl_add_u64 v[186:187], s[72:73], 0, v[158:159]
	ds_read_b128 v[150:153], v205 offset:32768
	ds_read_b128 v[174:177], v205 offset:33792
	ds_read_b128 v[178:181], v205 offset:34816
	ds_read_b128 v[182:185], v205 offset:35840
	ds_read_b128 v[194:197], v205 offset:36864
	ds_read_b128 v[206:209], v205 offset:37888
	ds_read_b128 v[210:213], v205 offset:38912
	ds_read_b128 v[214:217], v205 offset:39936
	global_load_lds_dwordx4 v[186:187], off
	v_lshl_add_u64 v[186:187], s[72:73], 0, v[156:157]
	s_mov_b32 m0, s26
	s_nop 0
	global_load_lds_dwordx4 v[186:187], off
	s_waitcnt lgkmcnt(8)
	s_barrier
	s_waitcnt lgkmcnt(0)
	s_setprio 1
	s_waitcnt lgkmcnt(0)
	v_mfma_f32_16x16x32_bf16 v[126:129], v[134:137], v[150:153], v[126:129]
	v_mfma_f32_16x16x32_bf16 v[118:121], v[142:145], v[150:153], v[118:121]
	v_mfma_f32_16x16x32_bf16 v[110:113], v[134:137], v[178:181], v[110:113]
	v_mfma_f32_16x16x32_bf16 v[102:105], v[142:145], v[178:181], v[102:105]
	v_mfma_f32_16x16x32_bf16 v[94:97], v[134:137], v[194:197], v[94:97]
	v_mfma_f32_16x16x32_bf16 v[86:89], v[142:145], v[194:197], v[86:89]
	v_mfma_f32_16x16x32_bf16 v[78:81], v[134:137], v[210:213], v[78:81]
	v_mfma_f32_16x16x32_bf16 v[70:73], v[142:145], v[210:213], v[70:73]
	v_mfma_f32_16x16x32_bf16 v[126:129], v[138:141], v[174:177], v[126:129]
	v_mfma_f32_16x16x32_bf16 v[118:121], v[146:149], v[174:177], v[118:121]
	v_mfma_f32_16x16x32_bf16 v[110:113], v[138:141], v[182:185], v[110:113]
	v_mfma_f32_16x16x32_bf16 v[102:105], v[146:149], v[182:185], v[102:105]
	v_mfma_f32_16x16x32_bf16 v[94:97], v[138:141], v[206:209], v[94:97]
	v_mfma_f32_16x16x32_bf16 v[86:89], v[146:149], v[206:209], v[86:89]
	v_mfma_f32_16x16x32_bf16 v[78:81], v[138:141], v[214:217], v[78:81]
	v_mfma_f32_16x16x32_bf16 v[70:73], v[146:149], v[214:217], v[70:73]
	s_setprio 0
	s_barrier
	s_add_i32 s55, 0, 0x1c000
	v_add_u32_e32 v186, s55, v201
	s_or_b32 s62, s54, 0x80
	s_add_i32 s17, s17, s21
	ds_read_b128 v[218:221], v186
	ds_read_b128 v[222:225], v186 offset:1024
	ds_read_b128 v[226:229], v186 offset:2048
	ds_read_b128 v[244:247], v186 offset:3072
	v_lshl_add_u64 v[186:187], v[160:161], 0, s[62:63]
	s_mov_b32 m0, s17
	s_nop 0
	global_load_lds_dwordx4 v[186:187], off
	v_lshl_add_u64 v[186:187], v[162:163], 0, s[62:63]
	s_add_i32 m0, s17, 0x2000
	s_nop 0
	global_load_lds_dwordx4 v[186:187], off
	s_barrier
	s_waitcnt lgkmcnt(0)
	s_setprio 1
	s_waitcnt lgkmcnt(0)
	v_mfma_f32_16x16x32_bf16 v[122:125], v[218:221], v[150:153], v[122:125]
	v_mfma_f32_16x16x32_bf16 v[114:117], v[226:229], v[150:153], v[114:117]
	v_mfma_f32_16x16x32_bf16 v[106:109], v[218:221], v[178:181], v[106:109]
	v_mfma_f32_16x16x32_bf16 v[98:101], v[226:229], v[178:181], v[98:101]
	v_mfma_f32_16x16x32_bf16 v[90:93], v[218:221], v[194:197], v[90:93]
	v_mfma_f32_16x16x32_bf16 v[82:85], v[226:229], v[194:197], v[82:85]
	v_mfma_f32_16x16x32_bf16 v[74:77], v[218:221], v[210:213], v[74:77]
	v_mfma_f32_16x16x32_bf16 v[66:69], v[226:229], v[210:213], v[66:69]
	v_mfma_f32_16x16x32_bf16 v[122:125], v[222:225], v[174:177], v[122:125]
	v_mfma_f32_16x16x32_bf16 v[114:117], v[244:247], v[174:177], v[114:117]
	v_mfma_f32_16x16x32_bf16 v[106:109], v[222:225], v[182:185], v[106:109]
	v_mfma_f32_16x16x32_bf16 v[98:101], v[244:247], v[182:185], v[98:101]
	v_mfma_f32_16x16x32_bf16 v[90:93], v[222:225], v[206:209], v[90:93]
	v_mfma_f32_16x16x32_bf16 v[82:85], v[244:247], v[206:209], v[82:85]
	v_mfma_f32_16x16x32_bf16 v[74:77], v[222:225], v[214:217], v[74:77]
	v_mfma_f32_16x16x32_bf16 v[66:69], v[244:247], v[214:217], v[66:69]
	s_setprio 0
	s_mov_b32 s17, s63
	s_mov_b32 m0, s27
	v_lshl_add_u64 v[186:187], v[164:165], 0, s[16:17]
	s_barrier
	ds_read_b128 v[150:153], v205 offset:49152
	ds_read_b128 v[174:177], v205 offset:50176
	ds_read_b128 v[178:181], v205 offset:51200
	ds_read_b128 v[182:185], v205 offset:52224
	ds_read_b128 v[194:197], v205 offset:53248
	ds_read_b128 v[206:209], v205 offset:54272
	ds_read_b128 v[210:213], v205 offset:55296
	ds_read_b128 v[214:217], v205 offset:56320
	global_load_lds_dwordx4 v[186:187], off
	v_lshl_add_u64 v[186:187], v[166:167], 0, s[16:17]
	s_mov_b32 m0, s28
	s_nop 0
	global_load_lds_dwordx4 v[186:187], off
	s_barrier
; #define PG8_STAGE(bufoff, gbase, soff, voff) do { _Pragma("unroll") for (int _i = 0; _i < 2; ++_i) \
;         __builtin_amdgcn_global_load_lds((const unsigned*)(((gbase) + (size_t)(unsigned)(soff)) + (voff)[_i]), (LAS unsigned*)(lds + (bufoff) + ldsw + _i * 8192), 16, 0, 0); } while (0)
; #define PG8_MMA(ai, bj, At, Bt) do { __builtin_amdgcn_s_setprio(1); _Pragma("unroll") for (int m = 0; m < 4; ++m) _Pragma("unroll") for (int n = 0; n < 2; ++n) _Pragma("unroll") for (int k = 0; k < 2; ++k) \
;         acc[ai][bj][m][n] = __builtin_amdgcn_mfma_f32_16x16x32_bf16(Bt[n][k], At[m][k], acc[ai][bj][m][n], 0, 0, 0); __builtin_amdgcn_s_setprio(0); } while (0)
; #define PG8_WAIT_V(n) asm volatile("s_waitcnt vmcnt(" #n ")" ::: "memory")
; #define PG8_WAIT_L(n) asm volatile("s_waitcnt lgkmcnt(" #n ")" ::: "memory")
; #define PG8_BAR __builtin_amdgcn_s_barrier()
; #define PG8_SCHED __builtin_amdgcn_sched_barrier(0)
; __device__ __forceinline__ void rstd8(float (&rs)[2][4], const float* ssp, int row0, int fq) {
;     f32x4 p[2][4];
; #pragma unroll
;     for (int ai = 0; ai < 2; ++ai)
; #pragma unroll
;         for (int m = 0; m < 4; ++m) p[ai][m] = *(const f32x4*)(ssp + (size_t)(row0 + ai * 128 + m * 16) * 16 + fq * 4);
; template <class Epi>
; __device__ __forceinline__ void gemm_phase(LAS unsigned char* lds, const Gemm g, const StaticOrder& S, const Epi& E, const int tid) {
;     ...
;             PG8_BAR; PG8_WAIT_L(0); PG8_MMA(1, 0, At, B0); PG8_BAR; PG8_SCHED;
;             PG8_STAGE(PG8_SB(1, 1), gB, b3 + hstepB, voffB);
;             PG8_WAIT_V(6); PG8_BAR; PG8_MMA(1, 1, At, B1); PG8_BAR;
;         }
;         E(acc, cur, wr, wc, fr, fq);
	s_waitcnt lgkmcnt(0)
	s_setprio 1
	s_waitcnt lgkmcnt(0)
	v_mfma_f32_16x16x32_bf16 v[62:65], v[134:137], v[150:153], v[62:65]
	v_mfma_f32_16x16x32_bf16 v[54:57], v[142:145], v[150:153], v[54:57]
	v_mfma_f32_16x16x32_bf16 v[46:49], v[134:137], v[178:181], v[46:49]
	v_mfma_f32_16x16x32_bf16 v[38:41], v[142:145], v[178:181], v[38:41]
	v_mfma_f32_16x16x32_bf16 v[30:33], v[134:137], v[194:197], v[30:33]
	v_mfma_f32_16x16x32_bf16 v[22:25], v[142:145], v[194:197], v[22:25]
	v_mfma_f32_16x16x32_bf16 v[14:17], v[134:137], v[210:213], v[14:17]
	v_mfma_f32_16x16x32_bf16 v[6:9], v[142:145], v[210:213], v[6:9]
	v_mfma_f32_16x16x32_bf16 v[62:65], v[138:141], v[174:177], v[62:65]
	v_mfma_f32_16x16x32_bf16 v[54:57], v[146:149], v[174:177], v[54:57]
	v_mfma_f32_16x16x32_bf16 v[46:49], v[138:141], v[182:185], v[46:49]
	v_mfma_f32_16x16x32_bf16 v[38:41], v[146:149], v[182:185], v[38:41]
	v_mfma_f32_16x16x32_bf16 v[30:33], v[138:141], v[206:209], v[30:33]
	v_mfma_f32_16x16x32_bf16 v[22:25], v[146:149], v[206:209], v[22:25]
	v_mfma_f32_16x16x32_bf16 v[14:17], v[138:141], v[214:217], v[14:17]
	v_mfma_f32_16x16x32_bf16 v[6:9], v[146:149], v[214:217], v[6:9]
	s_setprio 0
	s_barrier
	s_add_i32 s54, s54, 0x40080
	s_add_u32 s16, s8, s54
	s_addc_u32 s17, s9, 0
	s_add_i32 s54, s55, s21
	v_lshl_add_u64 v[134:135], s[16:17], 0, v[0:1]
	s_mov_b32 m0, s54
	s_nop 0
	global_load_lds_dwordx4 v[134:135], off
	v_lshl_add_u64 v[134:135], s[16:17], 0, v[154:155]
	s_add_i32 m0, s54, 0x2000
	s_nop 0
	global_load_lds_dwordx4 v[134:135], off
	s_waitcnt vmcnt(6)
	s_barrier
	s_setprio 1
	v_mfma_f32_16x16x32_bf16 v[58:61], v[218:221], v[150:153], v[58:61]
	v_mfma_f32_16x16x32_bf16 v[50:53], v[226:229], v[150:153], v[50:53]
	v_mfma_f32_16x16x32_bf16 v[42:45], v[218:221], v[178:181], v[42:45]
	v_mfma_f32_16x16x32_bf16 v[34:37], v[226:229], v[178:181], v[34:37]
	v_mfma_f32_16x16x32_bf16 v[26:29], v[218:221], v[194:197], v[26:29]
	v_mfma_f32_16x16x32_bf16 v[18:21], v[226:229], v[194:197], v[18:21]
	v_mfma_f32_16x16x32_bf16 v[10:13], v[218:221], v[210:213], v[10:13]
	v_mfma_f32_16x16x32_bf16 v[2:5], v[226:229], v[210:213], v[2:5]
	v_mfma_f32_16x16x32_bf16 v[58:61], v[222:225], v[174:177], v[58:61]
	v_mfma_f32_16x16x32_bf16 v[50:53], v[244:247], v[174:177], v[50:53]
	v_mfma_f32_16x16x32_bf16 v[42:45], v[222:225], v[182:185], v[42:45]
	v_mfma_f32_16x16x32_bf16 v[34:37], v[244:247], v[182:185], v[34:37]
	v_mfma_f32_16x16x32_bf16 v[26:29], v[222:225], v[206:209], v[26:29]
	v_mfma_f32_16x16x32_bf16 v[18:21], v[244:247], v[206:209], v[18:21]
	v_mfma_f32_16x16x32_bf16 v[10:13], v[222:225], v[214:217], v[10:13]
	v_mfma_f32_16x16x32_bf16 v[2:5], v[244:247], v[214:217], v[2:5]
	s_setprio 0
	s_add_i32 s53, s53, 2
	s_add_u32 s14, s14, 0x100
	s_addc_u32 s15, s15, 0
	s_cmp_gt_u32 s53, 13
	s_barrier
	s_cbranch_scc0 .LBB0_525
	v_bfe_u32 v193, v232, 4, 2
	v_lshlrev_b32_e32 v193, 4, v193
	v_lshl_add_u32 v193, v199, 6, v193
	v_add_u32_e32 v193, 0x22000, v193
	v_lshl_add_u32 v196, s44, 8, v199
	v_ashrrev_i32_e32 v197, 31, v196
	v_lshlrev_b64 v[130:131], 6, v[196:197]
	v_or_b32_e32 v194, 16, v196
	v_lshl_add_u64 v[130:131], v[168:169], 0, v[130:131]
	v_ashrrev_i32_e32 v195, 31, v194
	ds_read_b128 v[206:209], v193 offset:0
	v_lshlrev_b64 v[130:131], 6, v[194:195]
	v_lshl_add_u64 v[130:131], v[168:169], 0, v[130:131]
	ds_read_b128 v[210:213], v193 offset:1024
	v_or_b32_e32 v184, 32, v196
	v_ashrrev_i32_e32 v185, 31, v184
	v_lshlrev_b64 v[130:131], 6, v[184:185]
	v_or_b32_e32 v182, 48, v196
	v_lshl_add_u64 v[130:131], v[168:169], 0, v[130:131]
	v_ashrrev_i32_e32 v183, 31, v182
	ds_read_b128 v[150:153], v193 offset:2048
	v_lshlrev_b64 v[130:131], 6, v[182:183]
	v_lshl_add_u64 v[130:131], v[168:169], 0, v[130:131]
	ds_read_b128 v[146:149], v193 offset:3072
	v_add_u32_e32 v180, 0x80, v196
	v_ashrrev_i32_e32 v181, 31, v180
	v_lshlrev_b64 v[130:131], 6, v[180:181]
	v_add_u32_e32 v178, 0x90, v196
	v_lshl_add_u64 v[130:131], v[168:169], 0, v[130:131]
	v_ashrrev_i32_e32 v179, 31, v178
	ds_read_b128 v[142:145], v193 offset:8192
	v_lshlrev_b64 v[130:131], 6, v[178:179]
	v_lshl_add_u64 v[130:131], v[168:169], 0, v[130:131]
	ds_read_b128 v[138:141], v193 offset:9216
	v_add_u32_e32 v176, 0xa0, v196
	v_ashrrev_i32_e32 v177, 31, v176
	v_lshlrev_b64 v[130:131], 6, v[176:177]
	v_add_u32_e32 v174, 0xb0, v196
	v_lshl_add_u64 v[130:131], v[168:169], 0, v[130:131]
	v_ashrrev_i32_e32 v175, 31, v174
	ds_read_b128 v[134:137], v193 offset:10240
	v_lshlrev_b64 v[130:131], 6, v[174:175]
	v_lshl_add_u64 v[130:131], v[168:169], 0, v[130:131]
	ds_read_b128 v[130:133], v193 offset:11264
	v_and_b32_e32 v177, 64, v237
	v_xor_b32_e32 v175, 16, v237
	v_add_u32_e32 v179, 64, v177
	v_cmp_lt_i32_e32 vcc, v175, v179
	s_mov_b32 s6, 0x358637bd
	v_mov_b64_e32 v[202:203], s[6:7]
	v_cndmask_b32_e32 v175, v237, v175, vcc
	v_lshlrev_b32_e32 v177, 2, v175
	v_xor_b32_e32 v175, 32, v237
	v_cmp_lt_i32_e32 vcc, v175, v179
	s_mov_b32 s44, s34
	s_mov_b32 s16, s38
	v_cndmask_b32_e32 v175, v237, v175, vcc
	v_lshlrev_b32_e32 v175, 2, v175
	s_waitcnt lgkmcnt(0)
	v_mov_b32_e32 v186, v207
	v_mov_b32_e32 v187, v208
	v_mov_b32_e32 v207, v209
	v_mov_b32_e32 v188, v211
	v_mov_b32_e32 v189, v212
	v_mov_b32_e32 v211, v213
	v_pk_add_f32 v[186:187], v[186:187], v[206:207]
	v_pk_add_f32 v[188:189], v[188:189], v[210:211]
	v_mov_b32_e32 v191, v186
	v_mov_b32_e32 v190, v188
	v_mov_b32_e32 v186, v189
	v_pk_add_f32 v[186:187], v[190:191], v[186:187]
	ds_bpermute_b32 v189, v177, v187
	ds_bpermute_b32 v188, v177, v186
	s_waitcnt lgkmcnt(0)
	v_pk_add_f32 v[186:187], v[186:187], v[188:189]
	ds_bpermute_b32 v189, v175, v187
	ds_bpermute_b32 v188, v175, v186
	s_waitcnt lgkmcnt(0)
; __device__ __forceinline__ float sigmoidf_(float x) { return __builtin_amdgcn_rcpf(1.0f + __expf(-x)); }
; __device__ __forceinline__ void rstd8(float (&rs)[2][4], const float* ssp, int row0, int fq) {
;     ...
;         for (int m = 0; m < 4; ++m) p[ai][m] = *(const f32x4*)(ssp + (size_t)(row0 + ai * 128 + m * 16) * 16 + fq * 4);
; #pragma unroll
;     for (int ai = 0; ai < 2; ++ai)
; #pragma unroll
;         for (int m = 0; m < 4; ++m) { float t = (p[ai][m][0] + p[ai][m][1]) + (p[ai][m][2] + p[ai][m][3]); t += __shfl_xor(t, 16); t += __shfl_xor(t, 32); rs[ai][m] = rsqrtf(t * (1.0f / 1024.0f) + 1e-6f); }
;     __device__ __forceinline__ void operator()(const Acc& acc, const Unit& u, int wr, int wc, int fr, int fq) const {
;     ...
;             for (int m = 0; m < 4; ++m) { const int row = row0 + ai * 128 + m * 16; const float rs = rs8[ai][m]; f32x4 h[2];
; #pragma unroll
;                 for (int n = 0; n < 2; ++n) { const f32x4 gt = acc[ai][0][m][n] * rs, up = acc[ai][1][m][n] * rs;
; #pragma unroll
;                     for (int jj = 0; jj < 4; ++jj) h[n][jj] = gt[jj] * sigmoidf_(gt[jj]) * up[jj]; }
	v_pk_add_f32 v[186:187], v[186:187], v[188:189]
	s_nop 0
	v_pk_fma_f32 v[186:187], v[186:187], s[70:71], v[202:203] op_sel_hi:[1,0,0]
	s_nop 0
	v_mul_f32_e32 v179, 0x4b800000, v187
	v_cmp_gt_f32_e64 s[6:7], s76, v187
	v_cmp_gt_f32_e32 vcc, s76, v186
	s_nop 0
	v_cndmask_b32_e64 v179, v187, v179, s[6:7]
	v_rsq_f32_e32 v179, v179
	v_mov_b32_e32 v187, v152
	v_mov_b32_e32 v152, v147
	v_mov_b32_e32 v147, v149
	v_mul_f32_e32 v181, 0x45800000, v179
	v_cndmask_b32_e64 v200, v179, v181, s[6:7]
	v_mul_f32_e32 v179, 0x4b800000, v186
	v_cndmask_b32_e32 v179, v186, v179, vcc
	v_mov_b32_e32 v186, v151
	v_mov_b32_e32 v151, v153
	v_mov_b32_e32 v153, v148
	v_pk_add_f32 v[150:151], v[186:187], v[150:151]
	v_pk_add_f32 v[146:147], v[152:153], v[146:147]
	v_mov_b32_e32 v149, v150
	v_mov_b32_e32 v148, v146
	v_mov_b32_e32 v150, v147
	v_pk_add_f32 v[146:147], v[148:149], v[150:151]
	ds_bpermute_b32 v149, v177, v147
	ds_bpermute_b32 v148, v177, v146
	v_mov_b32_e32 v150, v143
	v_mov_b32_e32 v151, v144
	v_mov_b32_e32 v143, v145
	v_mov_b32_e32 v144, v139
	v_mov_b32_e32 v145, v140
	v_mov_b32_e32 v139, v141
	v_pk_add_f32 v[142:143], v[150:151], v[142:143]
	v_pk_add_f32 v[138:139], v[144:145], v[138:139]
	s_waitcnt lgkmcnt(0)
	v_pk_add_f32 v[146:147], v[146:147], v[148:149]
	v_mov_b32_e32 v140, v138
	v_mov_b32_e32 v141, v142
	v_mov_b32_e32 v142, v139
	ds_bpermute_b32 v149, v175, v147
	ds_bpermute_b32 v148, v175, v146
	v_pk_add_f32 v[138:139], v[140:141], v[142:143]
	ds_bpermute_b32 v141, v177, v139
	ds_bpermute_b32 v140, v177, v138
	v_mov_b32_e32 v142, v135
	v_mov_b32_e32 v143, v136
	v_mov_b32_e32 v135, v137
	v_mov_b32_e32 v136, v131
	v_mov_b32_e32 v137, v132
	v_mov_b32_e32 v131, v133
	s_waitcnt lgkmcnt(2)
	v_pk_add_f32 v[146:147], v[146:147], v[148:149]
	v_pk_add_f32 v[134:135], v[142:143], v[134:135]
	v_pk_add_f32 v[130:131], v[136:137], v[130:131]
	v_pk_fma_f32 v[146:147], v[146:147], s[70:71], v[202:203] op_sel_hi:[1,0,0]
	s_waitcnt lgkmcnt(0)
	v_pk_add_f32 v[138:139], v[138:139], v[140:141]
	v_mov_b32_e32 v132, v130
	v_mov_b32_e32 v133, v134
	v_mov_b32_e32 v134, v131
	v_mul_f32_e32 v148, 0x4b800000, v147
	v_cmp_gt_f32_e64 s[6:7], s76, v147
	ds_bpermute_b32 v141, v175, v139
	ds_bpermute_b32 v140, v175, v138
	v_pk_add_f32 v[130:131], v[132:133], v[134:135]
	v_cndmask_b32_e64 v147, v147, v148, s[6:7]
	ds_bpermute_b32 v133, v177, v131
	ds_bpermute_b32 v132, v177, v130
	v_rsq_f32_e32 v179, v179
	v_rsq_f32_e32 v147, v147
	s_waitcnt lgkmcnt(2)
	v_pk_add_f32 v[138:139], v[138:139], v[140:141]
	v_pk_mul_f32 v[126:127], v[126:127], v[200:201] op_sel_hi:[1,0]
	v_mul_f32_e32 v181, 0x45800000, v179
	v_mul_f32_e32 v148, 0x45800000, v147
	v_pk_fma_f32 v[138:139], v[138:139], s[70:71], v[202:203] op_sel_hi:[1,0,0]
	s_waitcnt lgkmcnt(0)
	v_pk_add_f32 v[130:131], v[130:131], v[132:133]
	v_cndmask_b32_e32 v198, v179, v181, vcc
	v_cmp_gt_f32_e32 vcc, s76, v146
	v_cndmask_b32_e64 v148, v147, v148, s[6:7]
	v_mul_f32_e32 v147, 0x4b800000, v146
	v_mul_f32_e32 v140, 0x4b800000, v139
	v_cmp_gt_f32_e64 s[6:7], s76, v139
	ds_bpermute_b32 v133, v175, v131
	ds_bpermute_b32 v132, v175, v130
	v_cndmask_b32_e32 v146, v146, v147, vcc
	v_cndmask_b32_e64 v139, v139, v140, s[6:7]
	v_rsq_f32_e32 v146, v146
	v_rsq_f32_e32 v139, v139
	s_waitcnt lgkmcnt(0)
	v_pk_add_f32 v[130:131], v[130:131], v[132:133]
	v_pk_mul_f32 v[122:123], v[122:123], v[200:201] op_sel_hi:[1,0]
	v_mul_f32_e32 v147, 0x45800000, v146
	v_mul_f32_e32 v140, 0x45800000, v139
	v_pk_fma_f32 v[130:131], v[130:131], s[70:71], v[202:203] op_sel_hi:[1,0,0]
	v_cndmask_b32_e32 v146, v146, v147, vcc
	v_cmp_gt_f32_e32 vcc, s76, v138
	v_cndmask_b32_e64 v140, v139, v140, s[6:7]
	v_mul_f32_e32 v139, 0x4b800000, v138
	v_mul_f32_e32 v132, 0x4b800000, v131
	v_cmp_gt_f32_e64 s[6:7], s76, v131
	v_cndmask_b32_e32 v138, v138, v139, vcc
	v_rsq_f32_e32 v138, v138
	v_cndmask_b32_e64 v131, v131, v132, s[6:7]
	v_rsq_f32_e32 v131, v131
	v_pk_mul_f32 v[124:125], v[124:125], v[200:201] op_sel_hi:[1,0]
	v_mul_f32_e32 v139, 0x45800000, v138
	v_cndmask_b32_e32 v138, v138, v139, vcc
	v_mul_f32_e32 v132, 0x45800000, v131
	v_cmp_gt_f32_e32 vcc, s76, v130
	v_cndmask_b32_e64 v132, v131, v132, s[6:7]
	v_mul_f32_e32 v131, 0x4b800000, v130
	v_cndmask_b32_e32 v130, v130, v131, vcc
	v_rsq_f32_e32 v130, v130
	v_pk_mul_f32 v[118:119], v[118:119], v[200:201] op_sel_hi:[1,0]
	v_pk_mul_f32 v[114:115], v[114:115], v[200:201] op_sel_hi:[1,0]
	v_lshl_or_b32 v134, s39, 7, v204
	v_mul_f32_e32 v131, 0x45800000, v130
	v_cndmask_b32_e32 v130, v130, v131, vcc
	v_mul_f32_e32 v131, 0xbfb8aa3b, v126
	v_exp_f32_e32 v131, v131
	v_pk_mul_f32 v[116:117], v[116:117], v[200:201] op_sel_hi:[1,0]
	v_ashrrev_i32_e32 v135, 31, v134
	v_pk_mul_f32 v[110:111], v[110:111], v[198:199] op_sel_hi:[1,0]
	v_add_f32_e32 v131, 1.0, v131
	v_rcp_f32_e32 v136, v131
	v_mul_f32_e32 v131, 0xbfb8aa3b, v127
	v_exp_f32_e32 v131, v131
	v_pk_mul_f32 v[106:107], v[106:107], v[198:199] op_sel_hi:[1,0]
	v_pk_mul_f32 v[108:109], v[108:109], v[198:199] op_sel_hi:[1,0]
	v_pk_mul_f32 v[102:103], v[102:103], v[198:199] op_sel_hi:[1,0]
	v_add_f32_e32 v131, 1.0, v131
	v_rcp_f32_e32 v137, v131
	v_pk_mul_f32 v[98:99], v[98:99], v[198:199] op_sel_hi:[1,0]
	v_pk_mul_f32 v[100:101], v[100:101], v[198:199] op_sel_hi:[1,0]
	v_pk_mul_f32 v[94:95], v[94:95], v[148:149] op_sel_hi:[1,0]
	v_pk_mul_f32 v[126:127], v[126:127], v[136:137]
	v_pk_mul_f32 v[90:91], v[90:91], v[148:149] op_sel_hi:[1,0]
	v_pk_mul_f32 v[122:123], v[122:123], v[126:127]
	v_pk_mul_f32 v[126:127], v[128:129], v[200:201] op_sel_hi:[1,0]
	v_pk_mul_f32 v[92:93], v[92:93], v[148:149] op_sel_hi:[1,0]
	v_mul_f32_e32 v128, 0xbfb8aa3b, v126
	v_mul_f32_e32 v129, 0xbfb8aa3b, v127
; __device__ __forceinline__ unsigned cvt_pk_bf16(float lo, float hi) { const f32x2 v = {lo, hi}; const bf16x2_t r = __builtin_convertvector(v, bf16x2_t); return __builtin_bit_cast(unsigned, r); }
; __device__ __forceinline__ float sigmoidf_(float x) { return __builtin_amdgcn_rcpf(1.0f + __expf(-x)); }
;     __device__ __forceinline__ void operator()(const Acc& acc, const Unit& u, int wr, int wc, int fr, int fq) const {
;     ...
;             for (int m = 0; m < 4; ++m) { const int row = row0 + ai * 128 + m * 16; const float rs = rs8[ai][m]; f32x4 h[2];
; #pragma unroll
;                 for (int n = 0; n < 2; ++n) { const f32x4 gt = acc[ai][0][m][n] * rs, up = acc[ai][1][m][n] * rs;
; #pragma unroll
;                     for (int jj = 0; jj < 4; ++jj) h[n][jj] = gt[jj] * sigmoidf_(gt[jj]) * up[jj]; }
;                 u32x4 w; w.x = cvt_pk_bf16(h[0][0], h[0][1]); w.y = cvt_pk_bf16(h[0][2], h[0][3]); w.z = cvt_pk_bf16(h[1][0], h[1][1]); w.w = cvt_pk_bf16(h[1][2], h[1][3]);
;                 *(u32x4*)(H + (size_t)row * FF + hc0) = w; }
	v_exp_f32_e32 v128, v128
	v_exp_f32_e32 v129, v129
	v_pk_mul_f32 v[86:87], v[86:87], v[148:149] op_sel_hi:[1,0]
	v_pk_mul_f32 v[82:83], v[82:83], v[148:149] op_sel_hi:[1,0]
	v_add_f32_e32 v128, 1.0, v128
	v_add_f32_e32 v129, 1.0, v129
	v_rcp_f32_e32 v128, v128
	v_rcp_f32_e32 v129, v129
	v_pk_mul_f32 v[84:85], v[84:85], v[148:149] op_sel_hi:[1,0]
	v_pk_mul_f32 v[78:79], v[78:79], v[146:147] op_sel_hi:[1,0]
	v_pk_mul_f32 v[74:75], v[74:75], v[146:147] op_sel_hi:[1,0]
	v_pk_mul_f32 v[126:127], v[126:127], v[128:129]
	v_pk_mul_f32 v[76:77], v[76:77], v[146:147] op_sel_hi:[1,0]
	v_pk_mul_f32 v[124:125], v[124:125], v[126:127]
	v_mul_f32_e32 v126, 0xbfb8aa3b, v118
	v_mul_f32_e32 v127, 0xbfb8aa3b, v119
	v_exp_f32_e32 v126, v126
	v_exp_f32_e32 v127, v127
	v_pk_mul_f32 v[70:71], v[70:71], v[146:147] op_sel_hi:[1,0]
	v_pk_mul_f32 v[66:67], v[66:67], v[146:147] op_sel_hi:[1,0]
	v_add_f32_e32 v126, 1.0, v126
	v_add_f32_e32 v127, 1.0, v127
	v_rcp_f32_e32 v126, v126
	v_rcp_f32_e32 v127, v127
	v_pk_mul_f32 v[68:69], v[68:69], v[146:147] op_sel_hi:[1,0]
	v_pk_mul_f32 v[62:63], v[62:63], v[140:141] op_sel_hi:[1,0]
	v_pk_mul_f32 v[58:59], v[58:59], v[140:141] op_sel_hi:[1,0]
	v_pk_mul_f32 v[118:119], v[118:119], v[126:127]
	v_pk_mul_f32 v[60:61], v[60:61], v[140:141] op_sel_hi:[1,0]
	v_pk_mul_f32 v[114:115], v[114:115], v[118:119]
	v_pk_mul_f32 v[118:119], v[120:121], v[200:201] op_sel_hi:[1,0]
	v_pk_mul_f32 v[54:55], v[54:55], v[140:141] op_sel_hi:[1,0]
	v_mul_f32_e32 v120, 0xbfb8aa3b, v118
	v_mul_f32_e32 v121, 0xbfb8aa3b, v119
	v_exp_f32_e32 v120, v120
	v_exp_f32_e32 v121, v121
	v_pk_mul_f32 v[50:51], v[50:51], v[140:141] op_sel_hi:[1,0]
	v_pk_mul_f32 v[52:53], v[52:53], v[140:141] op_sel_hi:[1,0]
	v_add_f32_e32 v120, 1.0, v120
	v_add_f32_e32 v121, 1.0, v121
	v_rcp_f32_e32 v120, v120
	v_rcp_f32_e32 v121, v121
	v_pk_mul_f32 v[46:47], v[46:47], v[138:139] op_sel_hi:[1,0]
	v_pk_mul_f32 v[42:43], v[42:43], v[138:139] op_sel_hi:[1,0]
	v_pk_mul_f32 v[44:45], v[44:45], v[138:139] op_sel_hi:[1,0]
	v_pk_mul_f32 v[118:119], v[118:119], v[120:121]
	v_cvt_pk_bf16_f32 v120, v114, v115
	v_pk_mul_f32 v[116:117], v[116:117], v[118:119]
	v_mov_b64_e32 v[114:115], s[12:13]
	v_cvt_pk_bf16_f32 v118, v122, v123
	v_cvt_pk_bf16_f32 v121, v116, v117
	v_mad_i64_i32 v[122:123], s[6:7], v196, s78, v[114:115]
	v_lshlrev_b64 v[116:117], 1, v[134:135]
	v_cvt_pk_bf16_f32 v119, v124, v125
	v_lshl_add_u64 v[122:123], v[122:123], 0, v[116:117]
	global_store_dwordx4 v[122:123], v[118:121], off
	v_pk_mul_f32 v[38:39], v[38:39], v[138:139] op_sel_hi:[1,0]
	v_pk_mul_f32 v[34:35], v[34:35], v[138:139] op_sel_hi:[1,0]
	v_mul_f32_e32 v118, 0xbfb8aa3b, v110
	v_mul_f32_e32 v119, 0xbfb8aa3b, v111
	v_exp_f32_e32 v118, v118
	v_exp_f32_e32 v119, v119
	v_pk_mul_f32 v[36:37], v[36:37], v[138:139] op_sel_hi:[1,0]
	v_pk_mul_f32 v[30:31], v[30:31], v[132:133] op_sel_hi:[1,0]
	v_add_f32_e32 v118, 1.0, v118
	v_add_f32_e32 v119, 1.0, v119
	v_rcp_f32_e32 v118, v118
	v_rcp_f32_e32 v119, v119
	v_pk_mul_f32 v[26:27], v[26:27], v[132:133] op_sel_hi:[1,0]
	v_pk_mul_f32 v[28:29], v[28:29], v[132:133] op_sel_hi:[1,0]
	v_pk_mul_f32 v[22:23], v[22:23], v[132:133] op_sel_hi:[1,0]
	v_pk_mul_f32 v[110:111], v[110:111], v[118:119]
	v_pk_mul_f32 v[18:19], v[18:19], v[132:133] op_sel_hi:[1,0]
	v_pk_mul_f32 v[106:107], v[106:107], v[110:111]
	v_pk_mul_f32 v[110:111], v[112:113], v[198:199] op_sel_hi:[1,0]
	v_pk_mul_f32 v[20:21], v[20:21], v[132:133] op_sel_hi:[1,0]
	v_mul_f32_e32 v112, 0xbfb8aa3b, v110
	v_mul_f32_e32 v113, 0xbfb8aa3b, v111
	v_exp_f32_e32 v112, v112
	v_exp_f32_e32 v113, v113
	v_pk_mul_f32 v[14:15], v[14:15], v[130:131] op_sel_hi:[1,0]
	v_pk_mul_f32 v[10:11], v[10:11], v[130:131] op_sel_hi:[1,0]
	v_add_f32_e32 v112, 1.0, v112
	v_add_f32_e32 v113, 1.0, v113
	v_rcp_f32_e32 v112, v112
	v_rcp_f32_e32 v113, v113
	v_pk_mul_f32 v[12:13], v[12:13], v[130:131] op_sel_hi:[1,0]
	v_pk_mul_f32 v[6:7], v[6:7], v[130:131] op_sel_hi:[1,0]
	v_pk_mul_f32 v[2:3], v[2:3], v[130:131] op_sel_hi:[1,0]
	v_pk_mul_f32 v[110:111], v[110:111], v[112:113]
	v_pk_mul_f32 v[4:5], v[4:5], v[130:131] op_sel_hi:[1,0]
	v_pk_mul_f32 v[108:109], v[108:109], v[110:111]
	v_mul_f32_e32 v110, 0xbfb8aa3b, v102
	v_mul_f32_e32 v111, 0xbfb8aa3b, v103
	v_exp_f32_e32 v110, v110
	v_exp_f32_e32 v111, v111
	s_and_b64 vcc, exec, s[4:5]
	s_mov_b32 s39, s31
	v_add_f32_e32 v110, 1.0, v110
	v_add_f32_e32 v111, 1.0, v111
	v_rcp_f32_e32 v110, v110
	v_rcp_f32_e32 v111, v111
	s_nop 0
	v_pk_mul_f32 v[102:103], v[102:103], v[110:111]
	s_nop 0
	v_pk_mul_f32 v[102:103], v[98:99], v[102:103]
	v_pk_mul_f32 v[98:99], v[104:105], v[198:199] op_sel_hi:[1,0]
	s_nop 0
	v_mul_f32_e32 v104, 0xbfb8aa3b, v98
	v_mul_f32_e32 v105, 0xbfb8aa3b, v99
	v_exp_f32_e32 v104, v104
	v_exp_f32_e32 v105, v105
	v_add_f32_e32 v104, 1.0, v104
	v_add_f32_e32 v105, 1.0, v105
	v_rcp_f32_e32 v104, v104
	v_rcp_f32_e32 v105, v105
	s_nop 0
	v_pk_mul_f32 v[98:99], v[98:99], v[104:105]
	s_nop 0
	v_pk_mul_f32 v[104:105], v[100:101], v[98:99]
	v_cvt_pk_bf16_f32 v100, v102, v103
	v_mad_i64_i32 v[102:103], s[6:7], v194, s78, v[114:115]
	v_cvt_pk_bf16_f32 v98, v106, v107
	v_cvt_pk_bf16_f32 v99, v108, v109
	v_cvt_pk_bf16_f32 v101, v104, v105
	v_lshl_add_u64 v[102:103], v[102:103], 0, v[116:117]
	global_store_dwordx4 v[102:103], v[98:101], off
	s_nop 1
	v_mul_f32_e32 v98, 0xbfb8aa3b, v94
	v_mul_f32_e32 v99, 0xbfb8aa3b, v95
	v_exp_f32_e32 v98, v98
	v_exp_f32_e32 v99, v99
	v_add_f32_e32 v98, 1.0, v98
	v_add_f32_e32 v99, 1.0, v99
	v_rcp_f32_e32 v98, v98
	v_rcp_f32_e32 v99, v99
	s_nop 0
	v_pk_mul_f32 v[94:95], v[94:95], v[98:99]
	s_nop 0
	v_pk_mul_f32 v[90:91], v[90:91], v[94:95]
	v_pk_mul_f32 v[94:95], v[96:97], v[148:149] op_sel_hi:[1,0]
; __device__ __forceinline__ unsigned cvt_pk_bf16(float lo, float hi) { const f32x2 v = {lo, hi}; const bf16x2_t r = __builtin_convertvector(v, bf16x2_t); return __builtin_bit_cast(unsigned, r); }
; __device__ __forceinline__ float sigmoidf_(float x) { return __builtin_amdgcn_rcpf(1.0f + __expf(-x)); }
;     __device__ __forceinline__ void operator()(const Acc& acc, const Unit& u, int wr, int wc, int fr, int fq) const {
;     ...
;                 for (int n = 0; n < 2; ++n) { const f32x4 gt = acc[ai][0][m][n] * rs, up = acc[ai][1][m][n] * rs;
; #pragma unroll
;                     for (int jj = 0; jj < 4; ++jj) h[n][jj] = gt[jj] * sigmoidf_(gt[jj]) * up[jj]; }
;                 u32x4 w; w.x = cvt_pk_bf16(h[0][0], h[0][1]); w.y = cvt_pk_bf16(h[0][2], h[0][3]); w.z = cvt_pk_bf16(h[1][0], h[1][1]); w.w = cvt_pk_bf16(h[1][2], h[1][3]);
;                 *(u32x4*)(H + (size_t)row * FF + hc0) = w; }
	s_nop 0
	v_mul_f32_e32 v96, 0xbfb8aa3b, v94
	v_mul_f32_e32 v97, 0xbfb8aa3b, v95
	v_exp_f32_e32 v96, v96
	v_exp_f32_e32 v97, v97
	v_add_f32_e32 v96, 1.0, v96
	v_add_f32_e32 v97, 1.0, v97
	v_rcp_f32_e32 v96, v96
	v_rcp_f32_e32 v97, v97
	s_nop 0
	v_pk_mul_f32 v[94:95], v[94:95], v[96:97]
	s_nop 0
	v_pk_mul_f32 v[92:93], v[92:93], v[94:95]
	v_mul_f32_e32 v94, 0xbfb8aa3b, v86
	v_mul_f32_e32 v95, 0xbfb8aa3b, v87
	v_exp_f32_e32 v94, v94
	v_exp_f32_e32 v95, v95
	v_add_f32_e32 v94, 1.0, v94
	v_add_f32_e32 v95, 1.0, v95
	v_rcp_f32_e32 v94, v94
	v_rcp_f32_e32 v95, v95
	s_nop 0
	v_pk_mul_f32 v[86:87], v[86:87], v[94:95]
	s_nop 0
	v_pk_mul_f32 v[86:87], v[82:83], v[86:87]
	v_pk_mul_f32 v[82:83], v[88:89], v[148:149] op_sel_hi:[1,0]
	s_nop 0
	v_mul_f32_e32 v88, 0xbfb8aa3b, v82
	v_mul_f32_e32 v89, 0xbfb8aa3b, v83
	v_exp_f32_e32 v88, v88
	v_exp_f32_e32 v89, v89
	v_add_f32_e32 v88, 1.0, v88
	v_add_f32_e32 v89, 1.0, v89
	v_rcp_f32_e32 v88, v88
	v_rcp_f32_e32 v89, v89
	s_nop 0
	v_pk_mul_f32 v[82:83], v[82:83], v[88:89]
	s_nop 0
	v_pk_mul_f32 v[88:89], v[84:85], v[82:83]
	v_cvt_pk_bf16_f32 v84, v86, v87
	v_mad_i64_i32 v[86:87], s[6:7], v184, s78, v[114:115]
	v_cvt_pk_bf16_f32 v82, v90, v91
	v_cvt_pk_bf16_f32 v83, v92, v93
	v_cvt_pk_bf16_f32 v85, v88, v89
	v_lshl_add_u64 v[86:87], v[86:87], 0, v[116:117]
	global_store_dwordx4 v[86:87], v[82:85], off
	s_nop 1
	v_mul_f32_e32 v82, 0xbfb8aa3b, v78
	v_mul_f32_e32 v83, 0xbfb8aa3b, v79
	v_exp_f32_e32 v82, v82
	v_exp_f32_e32 v83, v83
	v_add_f32_e32 v82, 1.0, v82
	v_add_f32_e32 v83, 1.0, v83
	v_rcp_f32_e32 v82, v82
	v_rcp_f32_e32 v83, v83
	s_nop 0
	v_pk_mul_f32 v[78:79], v[78:79], v[82:83]
	s_nop 0
	v_pk_mul_f32 v[74:75], v[74:75], v[78:79]
	v_pk_mul_f32 v[78:79], v[80:81], v[146:147] op_sel_hi:[1,0]
	s_nop 0
	v_mul_f32_e32 v80, 0xbfb8aa3b, v78
	v_mul_f32_e32 v81, 0xbfb8aa3b, v79
	v_exp_f32_e32 v80, v80
	v_exp_f32_e32 v81, v81
	v_add_f32_e32 v80, 1.0, v80
	v_add_f32_e32 v81, 1.0, v81
	v_rcp_f32_e32 v80, v80
	v_rcp_f32_e32 v81, v81
	s_nop 0
	v_pk_mul_f32 v[78:79], v[78:79], v[80:81]
	s_nop 0
	v_pk_mul_f32 v[76:77], v[76:77], v[78:79]
	v_mul_f32_e32 v78, 0xbfb8aa3b, v70
	v_mul_f32_e32 v79, 0xbfb8aa3b, v71
	v_exp_f32_e32 v78, v78
	v_exp_f32_e32 v79, v79
	v_add_f32_e32 v78, 1.0, v78
	v_add_f32_e32 v79, 1.0, v79
	v_rcp_f32_e32 v78, v78
	v_rcp_f32_e32 v79, v79
	s_nop 0
	v_pk_mul_f32 v[70:71], v[70:71], v[78:79]
	s_nop 0
	v_pk_mul_f32 v[70:71], v[66:67], v[70:71]
	v_pk_mul_f32 v[66:67], v[72:73], v[146:147] op_sel_hi:[1,0]
	s_nop 0
	v_mul_f32_e32 v72, 0xbfb8aa3b, v66
	v_mul_f32_e32 v73, 0xbfb8aa3b, v67
	v_exp_f32_e32 v72, v72
	v_exp_f32_e32 v73, v73
	v_add_f32_e32 v72, 1.0, v72
	v_add_f32_e32 v73, 1.0, v73
	v_rcp_f32_e32 v72, v72
	v_rcp_f32_e32 v73, v73
	s_nop 0
	v_pk_mul_f32 v[66:67], v[66:67], v[72:73]
	s_nop 0
	v_pk_mul_f32 v[72:73], v[68:69], v[66:67]
	v_cvt_pk_bf16_f32 v68, v70, v71
	v_mad_i64_i32 v[70:71], s[6:7], v182, s78, v[114:115]
	v_cvt_pk_bf16_f32 v66, v74, v75
	v_cvt_pk_bf16_f32 v67, v76, v77
	v_cvt_pk_bf16_f32 v69, v72, v73
	v_lshl_add_u64 v[70:71], v[70:71], 0, v[116:117]
	global_store_dwordx4 v[70:71], v[66:69], off
	s_nop 1
	v_mul_f32_e32 v66, 0xbfb8aa3b, v62
	v_mul_f32_e32 v67, 0xbfb8aa3b, v63
	v_exp_f32_e32 v66, v66
	v_exp_f32_e32 v67, v67
	v_add_f32_e32 v66, 1.0, v66
	v_add_f32_e32 v67, 1.0, v67
	v_rcp_f32_e32 v66, v66
	v_rcp_f32_e32 v67, v67
	s_nop 0
	v_pk_mul_f32 v[62:63], v[62:63], v[66:67]
	s_nop 0
	v_pk_mul_f32 v[58:59], v[58:59], v[62:63]
	v_pk_mul_f32 v[62:63], v[64:65], v[140:141] op_sel_hi:[1,0]
	s_nop 0
	v_mul_f32_e32 v64, 0xbfb8aa3b, v62
	v_mul_f32_e32 v65, 0xbfb8aa3b, v63
	v_exp_f32_e32 v64, v64
	v_exp_f32_e32 v65, v65
	v_add_f32_e32 v64, 1.0, v64
	v_add_f32_e32 v65, 1.0, v65
	v_rcp_f32_e32 v64, v64
	v_rcp_f32_e32 v65, v65
	s_nop 0
	v_pk_mul_f32 v[62:63], v[62:63], v[64:65]
	s_nop 0
	v_pk_mul_f32 v[60:61], v[60:61], v[62:63]
	v_mul_f32_e32 v62, 0xbfb8aa3b, v54
	v_mul_f32_e32 v63, 0xbfb8aa3b, v55
	v_exp_f32_e32 v62, v62
	v_exp_f32_e32 v63, v63
	v_add_f32_e32 v62, 1.0, v62
	v_add_f32_e32 v63, 1.0, v63
	v_rcp_f32_e32 v62, v62
	v_rcp_f32_e32 v63, v63
	s_nop 0
	v_pk_mul_f32 v[54:55], v[54:55], v[62:63]
	s_nop 0
	v_pk_mul_f32 v[54:55], v[50:51], v[54:55]
	v_pk_mul_f32 v[50:51], v[56:57], v[140:141] op_sel_hi:[1,0]
	s_nop 0
	v_mul_f32_e32 v56, 0xbfb8aa3b, v50
	v_mul_f32_e32 v57, 0xbfb8aa3b, v51
	v_exp_f32_e32 v56, v56
	v_exp_f32_e32 v57, v57
	v_add_f32_e32 v56, 1.0, v56
	v_add_f32_e32 v57, 1.0, v57
	v_rcp_f32_e32 v56, v56
	v_rcp_f32_e32 v57, v57
	s_nop 0
	v_pk_mul_f32 v[50:51], v[50:51], v[56:57]
	s_nop 0
	v_pk_mul_f32 v[56:57], v[52:53], v[50:51]
	v_cvt_pk_bf16_f32 v52, v54, v55
	v_mad_i64_i32 v[54:55], s[6:7], v180, s78, v[114:115]
	v_cvt_pk_bf16_f32 v50, v58, v59
	v_cvt_pk_bf16_f32 v51, v60, v61
	v_cvt_pk_bf16_f32 v53, v56, v57
	v_lshl_add_u64 v[54:55], v[54:55], 0, v[116:117]
	global_store_dwordx4 v[54:55], v[50:53], off
	s_nop 1
	v_mul_f32_e32 v50, 0xbfb8aa3b, v46
	v_mul_f32_e32 v51, 0xbfb8aa3b, v47
	v_exp_f32_e32 v50, v50
	v_exp_f32_e32 v51, v51
	v_add_f32_e32 v50, 1.0, v50
	v_add_f32_e32 v51, 1.0, v51
	v_rcp_f32_e32 v50, v50
	v_rcp_f32_e32 v51, v51
; __device__ __forceinline__ unsigned cvt_pk_bf16(float lo, float hi) { const f32x2 v = {lo, hi}; const bf16x2_t r = __builtin_convertvector(v, bf16x2_t); return __builtin_bit_cast(unsigned, r); }
; __device__ __forceinline__ float sigmoidf_(float x) { return __builtin_amdgcn_rcpf(1.0f + __expf(-x)); }
; #define PG8_WAIT_V(n) asm volatile("s_waitcnt vmcnt(" #n ")" ::: "memory")
; #define PG8_BAR __builtin_amdgcn_s_barrier()
; template <class Epi>
; __device__ __forceinline__ void gemm_phase(LAS unsigned char* lds, const Gemm g, const StaticOrder& S, const Epi& E, const int tid) {
;     ...
;     PG8_WAIT_V(0);
;     if (wr == 0) PG8_BAR;
;     PG8_BAR;
;     __device__ __forceinline__ void operator()(const Acc& acc, const Unit& u, int wr, int wc, int fr, int fq) const {
;     ...
;                 for (int n = 0; n < 2; ++n) { const f32x4 gt = acc[ai][0][m][n] * rs, up = acc[ai][1][m][n] * rs;
; #pragma unroll
;                     for (int jj = 0; jj < 4; ++jj) h[n][jj] = gt[jj] * sigmoidf_(gt[jj]) * up[jj]; }
;                 u32x4 w; w.x = cvt_pk_bf16(h[0][0], h[0][1]); w.y = cvt_pk_bf16(h[0][2], h[0][3]); w.z = cvt_pk_bf16(h[1][0], h[1][1]); w.w = cvt_pk_bf16(h[1][2], h[1][3]);
;                 *(u32x4*)(H + (size_t)row * FF + hc0) = w; }
	s_nop 0
	v_pk_mul_f32 v[46:47], v[46:47], v[50:51]
	s_nop 0
	v_pk_mul_f32 v[42:43], v[42:43], v[46:47]
	v_pk_mul_f32 v[46:47], v[48:49], v[138:139] op_sel_hi:[1,0]
	s_nop 0
	v_mul_f32_e32 v48, 0xbfb8aa3b, v46
	v_mul_f32_e32 v49, 0xbfb8aa3b, v47
	v_exp_f32_e32 v48, v48
	v_exp_f32_e32 v49, v49
	v_add_f32_e32 v48, 1.0, v48
	v_add_f32_e32 v49, 1.0, v49
	v_rcp_f32_e32 v48, v48
	v_rcp_f32_e32 v49, v49
	s_nop 0
	v_pk_mul_f32 v[46:47], v[46:47], v[48:49]
	s_nop 0
	v_pk_mul_f32 v[44:45], v[44:45], v[46:47]
	v_mul_f32_e32 v46, 0xbfb8aa3b, v38
	v_mul_f32_e32 v47, 0xbfb8aa3b, v39
	v_exp_f32_e32 v46, v46
	v_exp_f32_e32 v47, v47
	v_add_f32_e32 v46, 1.0, v46
	v_add_f32_e32 v47, 1.0, v47
	v_rcp_f32_e32 v46, v46
	v_rcp_f32_e32 v47, v47
	s_nop 0
	v_pk_mul_f32 v[38:39], v[38:39], v[46:47]
	s_nop 0
	v_pk_mul_f32 v[38:39], v[34:35], v[38:39]
	v_pk_mul_f32 v[34:35], v[40:41], v[138:139] op_sel_hi:[1,0]
	s_nop 0
	v_mul_f32_e32 v40, 0xbfb8aa3b, v34
	v_mul_f32_e32 v41, 0xbfb8aa3b, v35
	v_exp_f32_e32 v40, v40
	v_exp_f32_e32 v41, v41
	v_add_f32_e32 v40, 1.0, v40
	v_add_f32_e32 v41, 1.0, v41
	v_rcp_f32_e32 v40, v40
	v_rcp_f32_e32 v41, v41
	s_nop 0
	v_pk_mul_f32 v[34:35], v[34:35], v[40:41]
	s_nop 0
	v_pk_mul_f32 v[40:41], v[36:37], v[34:35]
	v_cvt_pk_bf16_f32 v36, v38, v39
	v_mad_i64_i32 v[38:39], s[6:7], v178, s78, v[114:115]
	v_cvt_pk_bf16_f32 v34, v42, v43
	v_cvt_pk_bf16_f32 v35, v44, v45
	v_cvt_pk_bf16_f32 v37, v40, v41
	v_lshl_add_u64 v[38:39], v[38:39], 0, v[116:117]
	global_store_dwordx4 v[38:39], v[34:37], off
	s_nop 1
	v_mul_f32_e32 v34, 0xbfb8aa3b, v30
	v_mul_f32_e32 v35, 0xbfb8aa3b, v31
	v_exp_f32_e32 v34, v34
	v_exp_f32_e32 v35, v35
	v_add_f32_e32 v34, 1.0, v34
	v_add_f32_e32 v35, 1.0, v35
	v_rcp_f32_e32 v34, v34
	v_rcp_f32_e32 v35, v35
	s_nop 0
	v_pk_mul_f32 v[30:31], v[30:31], v[34:35]
	s_nop 0
	v_pk_mul_f32 v[26:27], v[26:27], v[30:31]
	v_pk_mul_f32 v[30:31], v[32:33], v[132:133] op_sel_hi:[1,0]
	s_nop 0
	v_mul_f32_e32 v32, 0xbfb8aa3b, v30
	v_mul_f32_e32 v33, 0xbfb8aa3b, v31
	v_exp_f32_e32 v32, v32
	v_exp_f32_e32 v33, v33
	v_add_f32_e32 v32, 1.0, v32
	v_add_f32_e32 v33, 1.0, v33
	v_rcp_f32_e32 v32, v32
	v_rcp_f32_e32 v33, v33
	s_nop 0
	v_pk_mul_f32 v[30:31], v[30:31], v[32:33]
	s_nop 0
	v_pk_mul_f32 v[28:29], v[28:29], v[30:31]
	v_mul_f32_e32 v30, 0xbfb8aa3b, v22
	v_mul_f32_e32 v31, 0xbfb8aa3b, v23
	v_exp_f32_e32 v30, v30
	v_exp_f32_e32 v31, v31
	v_add_f32_e32 v30, 1.0, v30
	v_add_f32_e32 v31, 1.0, v31
	v_rcp_f32_e32 v30, v30
	v_rcp_f32_e32 v31, v31
	s_nop 0
	v_pk_mul_f32 v[22:23], v[22:23], v[30:31]
	s_nop 0
	v_pk_mul_f32 v[22:23], v[18:19], v[22:23]
	v_pk_mul_f32 v[18:19], v[24:25], v[132:133] op_sel_hi:[1,0]
	s_nop 0
	v_mul_f32_e32 v24, 0xbfb8aa3b, v18
	v_mul_f32_e32 v25, 0xbfb8aa3b, v19
	v_exp_f32_e32 v24, v24
	v_exp_f32_e32 v25, v25
	v_add_f32_e32 v24, 1.0, v24
	v_add_f32_e32 v25, 1.0, v25
	v_rcp_f32_e32 v24, v24
	v_rcp_f32_e32 v25, v25
	s_nop 0
	v_pk_mul_f32 v[18:19], v[18:19], v[24:25]
	s_nop 0
	v_pk_mul_f32 v[24:25], v[20:21], v[18:19]
	v_cvt_pk_bf16_f32 v20, v22, v23
	v_mad_i64_i32 v[22:23], s[6:7], v176, s78, v[114:115]
	v_cvt_pk_bf16_f32 v18, v26, v27
	v_cvt_pk_bf16_f32 v19, v28, v29
	v_cvt_pk_bf16_f32 v21, v24, v25
	v_lshl_add_u64 v[22:23], v[22:23], 0, v[116:117]
	global_store_dwordx4 v[22:23], v[18:21], off
	s_nop 1
	v_mul_f32_e32 v18, 0xbfb8aa3b, v14
	v_mul_f32_e32 v19, 0xbfb8aa3b, v15
	v_exp_f32_e32 v18, v18
	v_exp_f32_e32 v19, v19
	v_add_f32_e32 v18, 1.0, v18
	v_add_f32_e32 v19, 1.0, v19
	v_rcp_f32_e32 v18, v18
	v_rcp_f32_e32 v19, v19
	s_nop 0
	v_pk_mul_f32 v[14:15], v[14:15], v[18:19]
	s_nop 0
	v_pk_mul_f32 v[10:11], v[10:11], v[14:15]
	v_pk_mul_f32 v[14:15], v[16:17], v[130:131] op_sel_hi:[1,0]
	s_nop 0
	v_mul_f32_e32 v16, 0xbfb8aa3b, v14
	v_mul_f32_e32 v17, 0xbfb8aa3b, v15
	v_exp_f32_e32 v16, v16
	v_exp_f32_e32 v17, v17
	v_add_f32_e32 v16, 1.0, v16
	v_add_f32_e32 v17, 1.0, v17
	v_rcp_f32_e32 v16, v16
	v_rcp_f32_e32 v17, v17
	s_nop 0
	v_pk_mul_f32 v[14:15], v[14:15], v[16:17]
	s_nop 0
	v_pk_mul_f32 v[12:13], v[12:13], v[14:15]
	v_mul_f32_e32 v14, 0xbfb8aa3b, v6
	v_mul_f32_e32 v15, 0xbfb8aa3b, v7
	v_exp_f32_e32 v14, v14
	v_exp_f32_e32 v15, v15
	v_add_f32_e32 v14, 1.0, v14
	v_add_f32_e32 v15, 1.0, v15
	v_rcp_f32_e32 v14, v14
	v_rcp_f32_e32 v15, v15
	s_nop 0
	v_pk_mul_f32 v[6:7], v[6:7], v[14:15]
	s_nop 0
	v_pk_mul_f32 v[6:7], v[2:3], v[6:7]
	v_pk_mul_f32 v[2:3], v[8:9], v[130:131] op_sel_hi:[1,0]
	s_nop 0
	v_mul_f32_e32 v8, 0xbfb8aa3b, v2
	v_mul_f32_e32 v9, 0xbfb8aa3b, v3
	v_exp_f32_e32 v8, v8
	v_exp_f32_e32 v9, v9
	v_add_f32_e32 v8, 1.0, v8
	v_add_f32_e32 v9, 1.0, v9
	v_rcp_f32_e32 v8, v8
	v_rcp_f32_e32 v9, v9
	s_nop 0
	v_pk_mul_f32 v[2:3], v[2:3], v[8:9]
	s_nop 0
	v_pk_mul_f32 v[8:9], v[4:5], v[2:3]
	v_cvt_pk_bf16_f32 v4, v6, v7
	v_mad_i64_i32 v[6:7], s[6:7], v174, s78, v[114:115]
	v_cvt_pk_bf16_f32 v2, v10, v11
	v_cvt_pk_bf16_f32 v3, v12, v13
	v_cvt_pk_bf16_f32 v5, v8, v9
	v_lshl_add_u64 v[6:7], v[6:7], 0, v[116:117]
	s_mov_b32 s6, s35
	global_store_dwordx4 v[6:7], v[2:5], off
	s_cbranch_vccz .LBB0_522
	s_waitcnt vmcnt(0)
	s_cmpk_gt_u32 s20, 0xff
	s_cbranch_scc1 .LBB0_529
	s_barrier

; #define LAS __attribute__((address_space(3)))
; __global__ void __launch_bounds__(512) mega(Params P) {
;     extern __shared__ __attribute__((aligned(16))) unsigned char lds_raw[];
;     LAS unsigned char* lds = (LAS unsigned char*)lds_raw;
;     cg::grid_group grid = cg::this_grid();
;     volatile LAS unsigned* xst = (volatile LAS unsigned*)(lds + LDS_BYTES - 16);
	.amdhsa_kernel _Z4mega6Params
		.amdhsa_group_segment_fixed_size 16384
		.amdhsa_private_segment_fixed_size 0
		.amdhsa_kernarg_size 536
		.amdhsa_user_sgpr_count 2
		.amdhsa_user_sgpr_dispatch_ptr 0
		.amdhsa_user_sgpr_queue_ptr 0
		.amdhsa_user_sgpr_kernarg_segment_ptr 1
		.amdhsa_user_sgpr_dispatch_id 0
		.amdhsa_user_sgpr_kernarg_preload_length 0
		.amdhsa_user_sgpr_kernarg_preload_offset 0
		.amdhsa_user_sgpr_private_segment_size 0
		.amdhsa_uses_dynamic_stack 0
		.amdhsa_enable_private_segment 0
		.amdhsa_system_sgpr_workgroup_id_x 1
		.amdhsa_system_sgpr_workgroup_id_y 0
		.amdhsa_system_sgpr_workgroup_id_z 0
		.amdhsa_system_sgpr_workgroup_info 0
		.amdhsa_system_vgpr_workitem_id 2
		.amdhsa_next_free_vgpr 256
		.amdhsa_next_free_sgpr 102
		.amdhsa_accum_offset 256
		.amdhsa_reserve_vcc 1
		.amdhsa_float_round_mode_32 0
		.amdhsa_float_round_mode_16_64 0
		.amdhsa_float_denorm_mode_32 3
		.amdhsa_float_denorm_mode_16_64 3
		.amdhsa_dx10_clamp 1
		.amdhsa_ieee_mode 1
		.amdhsa_fp16_overflow 0
		.amdhsa_tg_split 0
		.amdhsa_exception_fp_ieee_invalid_op 0
		.amdhsa_exception_fp_denorm_src 0
		.amdhsa_exception_fp_ieee_div_zero 0
		.amdhsa_exception_fp_ieee_overflow 0
		.amdhsa_exception_fp_ieee_underflow 0
		.amdhsa_exception_fp_ieee_inexact 0
		.amdhsa_exception_int_div_zero 0
	.end_amdhsa_kernel

; #define LAS __attribute__((address_space(3)))
; __global__ void __launch_bounds__(512) mega(Params P) {
;     extern __shared__ __attribute__((aligned(16))) unsigned char lds_raw[];
;     LAS unsigned char* lds = (LAS unsigned char*)lds_raw;
;     cg::grid_group grid = cg::this_grid();
;     volatile LAS unsigned* xst = (volatile LAS unsigned*)(lds + LDS_BYTES - 16);
amdhsa.kernels:
  - .agpr_count:     0
    .args:
      - .offset:         0
        .size:           280
        .value_kind:     by_value
      - .offset:         280
        .size:           4
        .value_kind:     hidden_block_count_x
      - .offset:         284
        .size:           4
        .value_kind:     hidden_block_count_y
      - .offset:         288
        .size:           4
        .value_kind:     hidden_block_count_z
      - .offset:         292
        .size:           2
        .value_kind:     hidden_group_size_x
      - .offset:         294
        .size:           2
        .value_kind:     hidden_group_size_y
      - .offset:         296
        .size:           2
        .value_kind:     hidden_group_size_z
      - .offset:         298
        .size:           2
        .value_kind:     hidden_remainder_x
      - .offset:         300
        .size:           2
        .value_kind:     hidden_remainder_y
      - .offset:         302
        .size:           2
        .value_kind:     hidden_remainder_z
      - .offset:         320
        .size:           8
        .value_kind:     hidden_global_offset_x
      - .offset:         328
        .size:           8
        .value_kind:     hidden_global_offset_y
      - .offset:         336
        .size:           8
        .value_kind:     hidden_global_offset_z
      - .offset:         344
        .size:           2
        .value_kind:     hidden_grid_dims
      - .offset:         368
        .size:           8
        .value_kind:     hidden_multigrid_sync_arg
      - .offset:         400
        .size:           4
        .value_kind:     hidden_dynamic_lds_size
    .group_segment_fixed_size: 16384
    .kernarg_segment_align: 8
    .kernarg_segment_size: 536
    .language:       OpenCL C
    .language_version:
      - 2
      - 0
    .max_flat_workgroup_size: 512
    .name:           _Z4mega6Params
    .private_segment_fixed_size: 0
    .sgpr_count:     108
    .sgpr_spill_count: 210
    .symbol:         _Z4mega6Params.kd
    .uniform_work_group_size: 1
    .uses_dynamic_stack: false
    .vgpr_count:     256
    .vgpr_spill_count: 0
    .wavefront_size: 64
